# delta recurrence: KDT row permutation with xor swizzle: producer ds_write_b16 and consumer ds_read_b128 both bank-conflict free
# speedup vs baseline: 1.0036x; 1.0036x over previous
; #define LAS __attribute__((address_space(3)))
; __device__ __forceinline__ float* karg_out() { return *(volatile KAS fptr_t*)((const KAS char*)__builtin_amdgcn_kernarg_segment_ptr() + 256); }
; __device__ __forceinline__ unsigned char* karg_ws() { return *(volatile KAS ucptr_t*)((const KAS char*)__builtin_amdgcn_kernarg_segment_ptr() + 264); }
; #define lane opq(lane_now())
; #define tid opq((wave << 6) | lane_now())
; __device__ __forceinline__ void delta_pre_load(int b, int h, int c, int pt, DeltaPre& dp) {
;     const int bh = b * 8 + h, tt = pt >> 3, d0 = (pt & 7) * 16; const size_t t = (size_t)bh * SEQ + c * 32 + tt;
;     const size_t ro = ((size_t)b * SEQ + c * 32 + tt) * D + h * 128 + d0;
;     const bf16* Kt = (const bf16*)(karg_ws() + WS_Z + 3 * ZB) + ro; const bf16* Qt = (const bf16*)(karg_ws() + WS_H) + ro; const bf16* Vt = (const bf16*)(karg_ws() + WS_Z + 4 * ZB) + ro;
;     dp.k0 = *(const u32x4*)Kt; dp.k1 = *(const u32x4*)(Kt + 8); dp.q0 = *(const u32x4*)Qt; dp.q1 = *(const u32x4*)(Qt + 8); dp.v0 = *(const u32x4*)Vt; dp.v1 = *(const u32x4*)(Vt + 8);
;     const float* GC = (const float*)(karg_ws() + WS_GC);
;     dp.gct = GC[t]; dp.gl = GC[(size_t)bh * SEQ + c * 32 + 31]; dp.bet = ((const float*)(karg_ws() + WS_BETA))[t];
;     dp.nk = ((const float*)((const unsigned char*)karg_out() + OSB_NK))[t]; dp.nq = ((const float*)((const unsigned char*)karg_out() + OSB_NQ))[t];
;     dp.tia = *(const u32x4*)((const bf16*)(karg_ws() + (pt < 128 ? WS_TINV : WS_ATT)) + ((size_t)bh * 64 + c) * 1024 + (pt & 127) * 8);
; }
; __device__ __forceinline__ void delta_rec_task(const Params& P, LAS unsigned char* lds, int b, int h, int tid) {
;     const int lane = tid & 63, wave = tid >> 6, n = lane & 31, hh = lane >> 5, bh = b * 8 + h, pt = tid - 256;
;     const bool producer = wave >= 4;
;     constexpr int NC = SEQ / 32;
;     f32x16 S[4];
; #pragma unroll
;     for (int kb = 0; kb < 4; ++kb)
; #pragma unroll
;         for (int r = 0; r < 16; ++r) S[kb][r] = 0.f;
;     DeltaPre dcur, dnxt;
;     if (producer) { delta_pre_load(b, h, 0, pt, dcur); delta_pre_load(b, h, 1, pt, dnxt); delta_rec_stage(lds, pt, dcur); dcur = dnxt; }
.LBB0_1811:
	s_and_b64 vcc, exec, s[4:5]
	s_cbranch_vccz .LBB0_1821
	v_mov_b32_e32 v113, v167
	v_and_b32_e32 v221, 7, v113
	v_xor_b32_e32 v222, 0, v221
	v_mul_u32_u24_e32 v222, 0x50, v222
	v_xor_b32_e32 v223, 1, v221
	v_mul_u32_u24_e32 v223, 0x50, v223
	v_xor_b32_e32 v224, 2, v221
	v_mul_u32_u24_e32 v224, 0x50, v224
	v_xor_b32_e32 v225, 3, v221
	v_mul_u32_u24_e32 v225, 0x50, v225
	v_xor_b32_e32 v226, 4, v221
	v_mul_u32_u24_e32 v226, 0x50, v226
	v_xor_b32_e32 v227, 5, v221
	v_mul_u32_u24_e32 v227, 0x50, v227
	v_xor_b32_e32 v228, 6, v221
	v_mul_u32_u24_e32 v228, 0x50, v228
	v_xor_b32_e32 v229, 7, v221
	v_mul_u32_u24_e32 v229, 0x50, v229
	s_ashr_i32 s12, s2, 3
	v_ashrrev_i32_e32 v27, 6, v113
	s_and_b32 s18, s2, 7
	v_cmp_gt_i32_e64 s[8:9], 4, v27
	v_cmp_lt_i32_e32 vcc, 3, v27
	s_and_saveexec_b64 s[4:5], vcc
	s_cbranch_execz .LBB0_1816
	v_add_u32_e32 v54, 0xffffff00, v113
	s_ashr_i32 s13, s12, 31
	v_lshrrev_b32_e32 v24, 3, v54
	v_lshlrev_b32_e32 v0, 4, v113
	v_mov_b32_e32 v25, 0
	s_lshl_b64 s[6:7], s[12:13], 11
	v_and_b32_e32 v28, 0x70, v0
	v_lshl_add_u64 v[0:1], s[6:7], 0, v[24:25]
	s_load_dwordx2 s[6:7], s[0:1], 0x108
	v_lshlrev_b64 v[0:1], 10, v[0:1]
	s_lshl_b32 s3, s18, 7
	s_load_dwordx2 s[10:11], s[0:1], 0x108
	v_or3_b32 v0, v0, s3, v28
	v_lshlrev_b64 v[38:39], 1, v[0:1]
	s_load_dwordx2 s[14:15], s[0:1], 0x108
	s_waitcnt lgkmcnt(0)
	v_lshl_add_u64 v[0:1], s[6:7], 0, v[38:39]
	s_mov_b64 s[6:7], 0xb100000
	s_mov_b32 s13, 0xb100000
	v_lshl_add_u64 v[2:3], v[0:1], 0, s[6:7]
	v_add_co_u32_e32 v0, vcc, s13, v0
	v_lshl_add_u64 v[4:5], s[10:11], 0, v[38:39]
	s_nop 0
	v_addc_co_u32_e32 v1, vcc, 0, v1, vcc
	s_mov_b32 s19, 0x3000000
	global_load_dwordx4 v[20:23], v[0:1], off
	global_load_dwordx4 v[16:19], v[2:3], off offset:16
	v_add_co_u32_e32 v0, vcc, s19, v4
	s_mov_b64 s[10:11], 0x3000000
	v_lshl_add_u64 v[30:31], s[14:15], 0, v[38:39]
	v_addc_co_u32_e32 v1, vcc, 0, v5, vcc
	s_mov_b32 s28, 0xd140000
	v_lshl_add_u64 v[6:7], v[4:5], 0, s[10:11]
	global_load_dwordx4 v[12:15], v[0:1], off
	global_load_dwordx4 v[8:11], v[6:7], off offset:16
	v_add_co_u32_e32 v0, vcc, s28, v30
	s_mov_b64 s[16:17], 0xd140000
	s_nop 0
	v_addc_co_u32_e32 v1, vcc, 0, v31, vcc
	v_lshl_add_u64 v[32:33], v[30:31], 0, s[16:17]
	global_load_dwordx4 v[4:7], v[0:1], off
	s_nop 0
	global_load_dwordx4 v[0:3], v[32:33], off offset:16
	s_load_dwordx2 s[20:21], s[0:1], 0x108
	s_ashr_i32 s3, s2, 31
	s_lshl_b64 s[14:15], s[2:3], 11
	v_lshl_add_u64 v[30:31], s[14:15], 0, v[24:25]
	v_lshlrev_b64 v[32:33], 2, v[30:31]
	s_waitcnt lgkmcnt(0)
	s_add_u32 s20, s20, 0x2880000
	s_addc_u32 s21, s21, 0
	s_lshl_b64 s[22:23], s[2:3], 13
	v_lshl_add_u64 v[30:31], s[20:21], 0, v[32:33]
	s_add_u32 s20, s20, s22
	s_addc_u32 s21, s21, s23
	global_load_dword v29, v[30:31], off
	s_nop 0
	global_load_dword v30, v25, s[20:21] offset:124
	s_load_dwordx2 s[20:21], s[0:1], 0x108
	s_mov_b32 s29, 0x2f10000
	s_mov_b32 s30, 0x8a68000
	s_mov_b32 s31, 0x8ae8000
	s_movk_i32 s22, 0x180
	s_waitcnt lgkmcnt(0)
	v_lshl_add_u64 v[34:35], s[20:21], 0, v[32:33]
	v_add_co_u32_e32 v34, vcc, s29, v34
	v_mov_b32_e32 v41, v25
	s_nop 0
	v_addc_co_u32_e32 v35, vcc, 0, v35, vcc
	global_load_dword v26, v[34:35], off
	s_load_dwordx2 s[20:21], s[0:1], 0x100
	v_mov_b32_e32 v43, v25
	s_mov_b64 s[24:25], 0x10000
	v_lshl_add_u64 v[38:39], v[38:39], 0, s[24:25]
	s_or_b32 s14, s14, 32
	s_waitcnt lgkmcnt(0)
	v_lshl_add_u64 v[34:35], s[20:21], 0, v[32:33]
	v_add_co_u32_e32 v34, vcc, s30, v34
	s_nop 1
	v_addc_co_u32_e32 v35, vcc, 0, v35, vcc
	global_load_dword v31, v[34:35], off
	s_load_dwordx2 s[20:21], s[0:1], 0x100
	v_mov_b32_e32 v34, 0x1180000
	s_waitcnt lgkmcnt(0)
	v_lshl_add_u64 v[32:33], s[20:21], 0, v[32:33]
	v_add_co_u32_e32 v32, vcc, s31, v32
	s_nop 1
	v_addc_co_u32_e32 v33, vcc, 0, v33, vcc
	global_load_dword v32, v[32:33], off
	s_load_dwordx2 s[20:21], s[0:1], 0x108
	v_mov_b32_e32 v33, 0x1980000
	v_cmp_gt_u32_e32 vcc, s22, v113
	s_nop 1
	v_cndmask_b32_e32 v40, v33, v34, vcc
	s_waitcnt lgkmcnt(0)
	v_lshl_add_u64 v[34:35], s[20:21], 0, v[40:41]
	s_lshl_b64 s[20:21], s[2:3], 17
	v_lshlrev_b32_e32 v33, 4, v54
	v_lshl_add_u64 v[34:35], v[34:35], 0, s[20:21]
	v_and_b32_e32 v42, 0x7f0, v33
	v_lshl_add_u64 v[34:35], v[34:35], 0, v[42:43]
	global_load_dwordx4 v[34:37], v[34:35], off
	s_load_dwordx2 s[22:23], s[0:1], 0x108
	s_load_dwordx2 s[26:27], s[0:1], 0x108
	s_load_dwordx2 s[24:25], s[0:1], 0x108
	v_and_b32_e32 v33, 48, v33
	s_waitcnt lgkmcnt(0)
	v_lshl_add_u64 v[44:45], s[22:23], 0, v[38:39]
	v_lshl_add_u64 v[48:49], s[26:27], 0, v[38:39]
	v_lshl_add_u64 v[46:47], v[44:45], 0, s[6:7]
	v_lshl_add_u64 v[50:51], v[48:49], 0, s[10:11]
	v_add_co_u32_e64 v44, s[10:11], s13, v44
	v_lshl_add_u64 v[38:39], s[24:25], 0, v[38:39]
	s_nop 0
	v_addc_co_u32_e64 v45, s[10:11], 0, v45, s[10:11]
	global_load_dwordx4 v[84:87], v[44:45], off
	global_load_dwordx4 v[80:83], v[46:47], off offset:16
	v_add_co_u32_e64 v44, s[10:11], s19, v48
	v_lshl_add_u64 v[52:53], v[38:39], 0, s[16:17]
	s_nop 0
	v_addc_co_u32_e64 v45, s[10:11], 0, v49, s[10:11]
	v_add_co_u32_e64 v38, s[10:11], s28, v38
	global_load_dwordx4 v[76:79], v[44:45], off
	global_load_dwordx4 v[72:75], v[50:51], off offset:16
	v_addc_co_u32_e64 v39, s[10:11], 0, v39, s[10:11]
	global_load_dwordx4 v[68:71], v[38:39], off
	global_load_dwordx4 v[64:67], v[52:53], off offset:16
	s_load_dwordx2 s[6:7], s[0:1], 0x108
	v_lshl_add_u64 v[38:39], s[14:15], 0, v[24:25]
	v_lshlrev_b64 v[38:39], 2, v[38:39]
	s_waitcnt lgkmcnt(0)
	s_add_u32 s6, s6, 0x2880000
	s_addc_u32 s7, s7, 0
	s_lshl_b64 s[10:11], s[14:15], 2
	v_lshl_add_u64 v[44:45], s[6:7], 0, v[38:39]
	s_add_u32 s6, s6, s10
	s_addc_u32 s7, s7, s11
	global_load_dword v117, v[44:45], off
	global_load_dword v118, v25, s[6:7] offset:124
	s_load_dwordx2 s[6:7], s[0:1], 0x108
	s_waitcnt lgkmcnt(0)
; #define LAS __attribute__((address_space(3)))
; __device__ __forceinline__ float* karg_out() { return *(volatile KAS fptr_t*)((const KAS char*)__builtin_amdgcn_kernarg_segment_ptr() + 256); }
; __device__ __forceinline__ unsigned char* karg_ws() { return *(volatile KAS ucptr_t*)((const KAS char*)__builtin_amdgcn_kernarg_segment_ptr() + 264); }
; __device__ __forceinline__ void delta_pre_load(int b, int h, int c, int pt, DeltaPre& dp) {
;     ...
;     dp.k0 = *(const u32x4*)Kt; dp.k1 = *(const u32x4*)(Kt + 8); dp.q0 = *(const u32x4*)Qt; dp.q1 = *(const u32x4*)(Qt + 8); dp.v0 = *(const u32x4*)Vt; dp.v1 = *(const u32x4*)(Vt + 8);
;     const float* GC = (const float*)(karg_ws() + WS_GC);
;     dp.gct = GC[t]; dp.gl = GC[(size_t)bh * SEQ + c * 32 + 31]; dp.bet = ((const float*)(karg_ws() + WS_BETA))[t];
;     dp.nk = ((const float*)((const unsigned char*)karg_out() + OSB_NK))[t]; dp.nq = ((const float*)((const unsigned char*)karg_out() + OSB_NQ))[t];
;     dp.tia = *(const u32x4*)((const bf16*)(karg_ws() + (pt < 128 ? WS_TINV : WS_ATT)) + ((size_t)bh * 64 + c) * 1024 + (pt & 127) * 8);
; }
; __device__ __forceinline__ void delta_rec_stage(LAS unsigned char* buf, int pt, const DeltaPre& dp) {
;     const int tt = pt >> 3, dg = pt & 7, d0 = dg * 16;
;     { LAS bf16* dst = (LAS bf16*)(buf + (pt < 128 ? DR_TI : DR_AT)) + ((pt & 127) >> 2) * 40 + (pt & 3) * 8; *(LAS u32x4*)dst = dp.tia; }
;     if (pt == 0) *(LAS float*)(buf + DR_EGL) = __expf(dp.gl);
;     const float eg = __expf(dp.gct), ekd = __expf(dp.gl - dp.gct);
	v_lshl_add_u64 v[44:45], s[6:7], 0, v[38:39]
	v_add_co_u32_e64 v44, s[10:11], s29, v44
	s_nop 1
	v_addc_co_u32_e64 v45, s[10:11], 0, v45, s[10:11]
	global_load_dword v110, v[44:45], off
	s_load_dwordx2 s[6:7], s[0:1], 0x100
	s_waitcnt lgkmcnt(0)
	v_lshl_add_u64 v[44:45], s[6:7], 0, v[38:39]
	v_add_co_u32_e64 v44, s[10:11], s30, v44
	s_nop 1
	v_addc_co_u32_e64 v45, s[10:11], 0, v45, s[10:11]
	global_load_dword v119, v[44:45], off
	s_load_dwordx2 s[6:7], s[0:1], 0x100
	s_waitcnt lgkmcnt(0)
	v_lshl_add_u64 v[38:39], s[6:7], 0, v[38:39]
	v_add_co_u32_e64 v38, s[10:11], s31, v38
	s_nop 1
	v_addc_co_u32_e64 v39, s[10:11], 0, v39, s[10:11]
	global_load_dword v120, v[38:39], off
	s_load_dwordx2 s[6:7], s[0:1], 0x108
	s_waitcnt lgkmcnt(0)
	v_lshl_add_u64 v[38:39], s[6:7], 0, v[40:41]
	v_lshl_add_u64 v[38:39], v[38:39], 0, s[20:21]
	v_lshl_add_u64 v[38:39], v[38:39], 0, v[42:43]
	global_load_dwordx4 v[88:91], v[38:39], off offset:2048
	v_mov_b32_e32 v38, 0x7600
	v_mov_b32_e32 v39, 0x6c00
	v_cndmask_b32_e32 v38, v38, v39, vcc
	v_bfe_u32 v39, v113, 2, 5
	v_add_u32_e32 v38, 0, v38
	v_mul_u32_u24_e32 v39, 0x50, v39
	v_add3_u32 v33, v38, v39, v33
	v_cmp_eq_u32_e32 vcc, 0, v54
	s_waitcnt vmcnt(12)
	ds_write_b128 v33, v[34:37]
	s_and_saveexec_b64 s[6:7], vcc
	s_cbranch_execz .LBB0_1815
	v_mul_f32_e32 v33, 0x3fb8aa3b, v30
	v_exp_f32_e32 v33, v33
	ds_write_b32 v25, v33 offset:49664
; #define LAS __attribute__((address_space(3)))
; __device__ __forceinline__ unsigned f2bf(float f) { return pk2(f, f) & 0xffffu; }
; __device__ __forceinline__ void unpack8(const u32x4 u, float* x) { x[0] = bflo(u.x); x[1] = bfhi(u.x); x[2] = bflo(u.y); x[3] = bfhi(u.y); x[4] = bflo(u.z); x[5] = bfhi(u.z); x[6] = bflo(u.w); x[7] = bfhi(u.w); }
; __device__ __forceinline__ int perm16(int e) { return (e & ~12) | ((e >> 1) & 4) | ((e << 1) & 8); }
; __device__ __forceinline__ void delta_rec_stage(LAS unsigned char* buf, int pt, const DeltaPre& dp) {
;     const int tt = pt >> 3, dg = pt & 7, d0 = dg * 16;
;     { LAS bf16* dst = (LAS bf16*)(buf + (pt < 128 ? DR_TI : DR_AT)) + ((pt & 127) >> 2) * 40 + (pt & 3) * 8; *(LAS u32x4*)dst = dp.tia; }
;     if (pt == 0) *(LAS float*)(buf + DR_EGL) = __expf(dp.gl);
;     const float eg = __expf(dp.gct), ekd = __expf(dp.gl - dp.gct);
;     const float fq = dp.nq * eg, fkb = dp.nk * dp.bet * eg, fkd = dp.nk * ekd, bet = dp.bet;
;     float k[16], q[16], v[16];
;     unpack8(dp.k0, k); unpack8(dp.k1, k + 8); unpack8(dp.q0, q); unpack8(dp.q1, q + 8); unpack8(dp.v0, v); unpack8(dp.v1, v + 8);
;     LAS bf16* KB = (LAS bf16*)(buf + DR_KB) + tt * 136 + d0; LAS bf16* QD = (LAS bf16*)(buf + DR_QD) + tt * 136 + d0;
;     *(LAS bf16x8*)KB = pack8(k[0] * fkb, k[1] * fkb, k[2] * fkb, k[3] * fkb, k[8] * fkb, k[9] * fkb, k[10] * fkb, k[11] * fkb);
;     *(LAS bf16x8*)(KB + 8) = pack8(k[4] * fkb, k[5] * fkb, k[6] * fkb, k[7] * fkb, k[12] * fkb, k[13] * fkb, k[14] * fkb, k[15] * fkb);
;     *(LAS bf16x8*)QD = pack8(q[0] * fq, q[1] * fq, q[2] * fq, q[3] * fq, q[8] * fq, q[9] * fq, q[10] * fq, q[11] * fq);
;     *(LAS bf16x8*)(QD + 8) = pack8(q[4] * fq, q[5] * fq, q[6] * fq, q[7] * fq, q[12] * fq, q[13] * fq, q[14] * fq, q[15] * fq);
;     LAS bf16* KDT = (LAS bf16*)(buf + DR_KDT) + d0 * 40 + perm16(tt);
; #pragma unroll
;     for (int e = 0; e < 16; ++e) KDT[e * 40] = (bf16)f2bf(k[e] * fkd);
;     LAS float* VB = (LAS float*)(buf + DR_VB) + tt * 132 + d0;
; #pragma unroll
;     for (int e4 = 0; e4 < 4; ++e4) *(LAS f32x4*)(VB + 4 * e4) = (f32x4){v[4 * e4] * bet, v[4 * e4 + 1] * bet, v[4 * e4 + 2] * bet, v[4 * e4 + 3] * bet};
; }
.LBB0_1815:
	s_or_b64 exec, exec, s[6:7]
	v_mul_f32_e32 v25, 0x3fb8aa3b, v29
	v_sub_f32_e32 v29, v30, v29
	v_mul_f32_e32 v29, 0x3fb8aa3b, v29
	v_exp_f32_e32 v25, v25
	v_exp_f32_e32 v29, v29
	v_mul_f32_e32 v30, v26, v31
	s_movk_i32 s3, 0x110
	v_mul_f32_e32 v34, v25, v32
	v_mul_f32_e32 v36, v25, v30
	v_mul_f32_e32 v25, v29, v31
	v_mul_lo_u32 v29, v24, s3
	v_lshlrev_b32_e32 v38, 16, v20
	v_and_b32_e32 v39, 0xffff0000, v20
	v_lshlrev_b32_e32 v20, 16, v21
	v_and_b32_e32 v21, 0xffff0000, v21
	v_lshlrev_b32_e32 v40, 16, v16
	v_and_b32_e32 v41, 0xffff0000, v16
	v_lshlrev_b32_e32 v44, 16, v17
	v_and_b32_e32 v45, 0xffff0000, v17
	v_add_u32_e32 v29, 0, v29
	v_pk_mul_f32 v[30:31], v[36:37], v[38:39] op_sel_hi:[0,1]
	v_pk_mul_f32 v[32:33], v[36:37], v[20:21] op_sel_hi:[0,1]
	v_pk_mul_f32 v[42:43], v[36:37], v[40:41] op_sel_hi:[0,1]
	v_pk_mul_f32 v[16:17], v[36:37], v[44:45] op_sel_hi:[0,1]
	v_lshl_add_u32 v35, v28, 1, v29
	v_cvt_pk_bf16_f32 v30, v30, v31
	v_cvt_pk_bf16_f32 v31, v32, v33
	v_cvt_pk_bf16_f32 v32, v42, v43
	v_cvt_pk_bf16_f32 v33, v16, v17
	ds_write_b128 v35, v[30:33]
	v_lshlrev_b32_e32 v30, 16, v22
	v_and_b32_e32 v31, 0xffff0000, v22
	v_lshlrev_b32_e32 v22, 16, v23
	v_and_b32_e32 v23, 0xffff0000, v23
	v_lshlrev_b32_e32 v42, 16, v18
	v_and_b32_e32 v43, 0xffff0000, v18
	v_lshlrev_b32_e32 v48, 16, v19
	v_and_b32_e32 v49, 0xffff0000, v19
	v_pk_mul_f32 v[16:17], v[36:37], v[30:31] op_sel_hi:[0,1]
	v_pk_mul_f32 v[32:33], v[36:37], v[22:23] op_sel_hi:[0,1]
	v_pk_mul_f32 v[46:47], v[36:37], v[42:43] op_sel_hi:[0,1]
	v_pk_mul_f32 v[36:37], v[36:37], v[48:49] op_sel_hi:[0,1]
	v_cvt_pk_bf16_f32 v16, v16, v17
	v_cvt_pk_bf16_f32 v17, v32, v33
	v_cvt_pk_bf16_f32 v18, v46, v47
	v_cvt_pk_bf16_f32 v19, v36, v37
	ds_write_b128 v35, v[16:19] offset:16
	v_lshlrev_b32_e32 v16, 16, v12
	v_and_b32_e32 v17, 0xffff0000, v12
	v_lshlrev_b32_e32 v12, 16, v13
	v_and_b32_e32 v13, 0xffff0000, v13
	v_lshlrev_b32_e32 v18, 16, v8
	v_and_b32_e32 v19, 0xffff0000, v8
	v_lshlrev_b32_e32 v8, 16, v9
	v_and_b32_e32 v9, 0xffff0000, v9
	v_pk_mul_f32 v[16:17], v[34:35], v[16:17] op_sel_hi:[0,1]
	v_pk_mul_f32 v[12:13], v[34:35], v[12:13] op_sel_hi:[0,1]
	v_pk_mul_f32 v[18:19], v[34:35], v[18:19] op_sel_hi:[0,1]
	v_pk_mul_f32 v[8:9], v[34:35], v[8:9] op_sel_hi:[0,1]
	v_cvt_pk_bf16_f32 v16, v16, v17
	v_cvt_pk_bf16_f32 v17, v12, v13
	v_cvt_pk_bf16_f32 v18, v18, v19
	v_cvt_pk_bf16_f32 v19, v8, v9
	v_lshlrev_b32_e32 v8, 16, v14
	v_and_b32_e32 v9, 0xffff0000, v14
	v_lshlrev_b32_e32 v12, 16, v15
	v_and_b32_e32 v13, 0xffff0000, v15
	v_lshlrev_b32_e32 v14, 16, v10
	v_and_b32_e32 v15, 0xffff0000, v10
	v_lshlrev_b32_e32 v10, 16, v11
	v_and_b32_e32 v11, 0xffff0000, v11
	ds_write_b128 v35, v[16:19] offset:8704
	v_pk_mul_f32 v[8:9], v[34:35], v[8:9] op_sel_hi:[0,1]
	v_pk_mul_f32 v[12:13], v[34:35], v[12:13] op_sel_hi:[0,1]
	v_pk_mul_f32 v[14:15], v[34:35], v[14:15] op_sel_hi:[0,1]
	v_pk_mul_f32 v[16:17], v[34:35], v[10:11] op_sel_hi:[0,1]
	v_cvt_pk_bf16_f32 v8, v8, v9
	v_cvt_pk_bf16_f32 v9, v12, v13
	v_cvt_pk_bf16_f32 v10, v14, v15
	v_cvt_pk_bf16_f32 v11, v16, v17
	ds_write_b128 v35, v[8:11] offset:8720
	v_lshrrev_b32_e32 v10, 3, v113
	v_mov_b32_e32 v8, 0
	v_and_b32_e32 v10, 8, v10
	v_and_b32_e32 v9, 0x1ffffff3, v24
	v_add3_u32 v8, 0, v8, v10
	v_lshlrev_b32_e32 v10, 2, v24
	v_lshlrev_b32_e32 v9, 1, v9
	v_and_b32_e32 v10, 16, v10
	v_add3_u32 v8, v8, v9, v10
	v_mul_f32_e32 v9, v25, v38
	v_cvt_pk_bf16_f32 v9, v9, s0
	v_add_u32_e32 v230, v8, v222
	v_add_u32_e32 v231, v8, v223
	v_add_u32_e32 v232, v8, v224
	v_add_u32_e32 v233, v8, v225
	v_add_u32_e32 v234, v8, v226
	v_add_u32_e32 v235, v8, v227
	v_add_u32_e32 v236, v8, v228
	v_add_u32_e32 v237, v8, v229
	ds_write_b16 v230, v9 offset:17408
	v_mul_f32_e32 v9, v25, v39
	v_cvt_pk_bf16_f32 v9, v9, s0
	ds_write_b16 v231, v9 offset:18048
	v_mul_f32_e32 v9, v25, v20
	v_cvt_pk_bf16_f32 v9, v9, s0
	ds_write_b16 v232, v9 offset:18688
	v_mul_f32_e32 v9, v25, v21
	v_cvt_pk_bf16_f32 v9, v9, s0
	ds_write_b16 v233, v9 offset:19328
	v_mul_f32_e32 v9, v25, v30
	v_cvt_pk_bf16_f32 v9, v9, s0
	ds_write_b16 v234, v9 offset:19968
	v_mul_f32_e32 v9, v25, v31
	v_cvt_pk_bf16_f32 v9, v9, s0
	ds_write_b16 v235, v9 offset:20608
	v_mul_f32_e32 v9, v25, v22
	v_cvt_pk_bf16_f32 v9, v9, s0
	ds_write_b16 v236, v9 offset:21248
	v_mul_f32_e32 v9, v25, v23
	v_cvt_pk_bf16_f32 v9, v9, s0
	ds_write_b16 v237, v9 offset:21888
	v_mul_f32_e32 v9, v25, v40
	v_cvt_pk_bf16_f32 v9, v9, s0
	ds_write_b16 v230, v9 offset:22528
	v_mul_f32_e32 v9, v25, v41
	v_cvt_pk_bf16_f32 v9, v9, s0
	ds_write_b16 v231, v9 offset:23168
	v_mul_f32_e32 v9, v25, v44
	v_cvt_pk_bf16_f32 v9, v9, s0
	ds_write_b16 v232, v9 offset:23808
	v_mul_f32_e32 v9, v25, v45
	v_cvt_pk_bf16_f32 v9, v9, s0
	ds_write_b16 v233, v9 offset:24448
	v_mul_f32_e32 v9, v25, v42
	v_cvt_pk_bf16_f32 v9, v9, s0
	ds_write_b16 v234, v9 offset:25088
	v_mul_f32_e32 v9, v25, v43
	v_cvt_pk_bf16_f32 v9, v9, s0
	ds_write_b16 v235, v9 offset:25728
	v_mul_f32_e32 v9, v25, v48
	v_cvt_pk_bf16_f32 v9, v9, s0
	ds_write_b16 v236, v9 offset:26368
	v_mul_f32_e32 v9, v25, v49
	v_cvt_pk_bf16_f32 v9, v9, s0
	ds_write_b16 v237, v9 offset:27008
	v_lshlrev_b32_e32 v8, 8, v24
	v_lshlrev_b32_e32 v9, 2, v28
	v_add3_u32 v12, v29, v8, v9
	v_lshlrev_b32_e32 v8, 16, v4
	v_and_b32_e32 v9, 0xffff0000, v4
	v_lshlrev_b32_e32 v4, 16, v5
	v_and_b32_e32 v5, 0xffff0000, v5
	v_pk_mul_f32 v[10:11], v[26:27], v[4:5] op_sel_hi:[0,1]
	v_lshlrev_b32_e32 v4, 16, v6
	v_and_b32_e32 v5, 0xffff0000, v6
	v_lshlrev_b32_e32 v6, 16, v7
	v_and_b32_e32 v7, 0xffff0000, v7
	v_pk_mul_f32 v[4:5], v[26:27], v[4:5] op_sel_hi:[0,1]
	v_pk_mul_f32 v[6:7], v[26:27], v[6:7] op_sel_hi:[0,1]
	ds_write_b128 v12, v[4:7] offset:32784
	v_lshlrev_b32_e32 v4, 16, v0
	v_and_b32_e32 v5, 0xffff0000, v0
	v_lshlrev_b32_e32 v0, 16, v1
	v_and_b32_e32 v1, 0xffff0000, v1
	v_pk_mul_f32 v[6:7], v[26:27], v[0:1] op_sel_hi:[0,1]
	v_lshlrev_b32_e32 v0, 16, v2
	v_and_b32_e32 v1, 0xffff0000, v2
	v_lshlrev_b32_e32 v2, 16, v3
	v_and_b32_e32 v3, 0xffff0000, v3
	v_pk_mul_f32 v[8:9], v[26:27], v[8:9] op_sel_hi:[0,1]
	v_pk_mul_f32 v[4:5], v[26:27], v[4:5] op_sel_hi:[0,1]
	v_pk_mul_f32 v[0:1], v[26:27], v[0:1] op_sel_hi:[0,1]
	v_pk_mul_f32 v[2:3], v[26:27], v[2:3] op_sel_hi:[0,1]
	ds_write_b128 v12, v[8:11] offset:32768
	ds_write_b128 v12, v[4:7] offset:32800
	ds_write_b128 v12, v[0:3] offset:32816

; #define LAS __attribute__((address_space(3)))
; __device__ __forceinline__ int opq(int x) { asm volatile("" : "+v"(x)); return x; }
; #define lane opq(lane_now())
; #define tid opq((wave << 6) | lane_now())
; __device__ __forceinline__ void delta_rec_task(const Params& P, LAS unsigned char* lds, int b, int h, int tid) {
;     ...
;         const int lane = opq(tid) & 63, n = lane & 31, hh = lane >> 5;
;         for (int c = 0; c < NC; ++c) {
;             LAS unsigned char* buf = lds + (c & 1) * DR_BUF;
;             const int vb = wave;
;             bf16x8 SB[8];
; #pragma unroll
;             for (int s = 0; s < 8; ++s) { const int kb = s >> 1, o = 8 * (s & 1); SB[s] = pack8(S[kb][o], S[kb][o + 1], S[kb][o + 2], S[kb][o + 3], S[kb][o + 4], S[kb][o + 5], S[kb][o + 6], S[kb][o + 7]); }
;             f32x16 X1, P1;
; #pragma unroll
;             for (int r = 0; r < 16; ++r) { X1[r] = 0.f; P1[r] = 0.f; }
;             const LAS bf16* KB = (const LAS bf16*)(buf + DR_KB) + n * 136 + 8 * hh; const LAS bf16* QD = (const LAS bf16*)(buf + DR_QD) + n * 136 + 8 * hh;
; #pragma unroll
;             for (int s = 0; s < 8; ++s) { X1 = __builtin_amdgcn_mfma_f32_32x32x16_bf16(*(const LAS bf16x8*)(KB + 16 * s), SB[s], X1, 0, 0, 0);
;                 P1 = __builtin_amdgcn_mfma_f32_32x32x16_bf16(*(const LAS bf16x8*)(QD + 16 * s), SB[s], P1, 0, 0, 0); }
.LBB0_1832:
	v_mov_b32_e32 v0, v113
	s_add_i32 s5, 0, 0x18420
	v_and_b32_e32 v1, 31, v0
	v_and_b32_e32 v183, 15, v1
	v_lshrrev_b32_e32 v184, 4, v1
	v_and_b32_e32 v185, 7, v1
	v_add_u32_e32 v175, 0, v184
	v_xor_b32_e32 v175, v175, v185
	v_lshl_add_u32 v175, v183, 3, v175
	v_mul_u32_u24_e32 v175, 0x50, v175
	v_add_u32_e32 v176, 2, v184
	v_xor_b32_e32 v176, v176, v185
	v_lshl_add_u32 v176, v183, 3, v176
	v_mul_u32_u24_e32 v176, 0x50, v176
	v_add_u32_e32 v177, 4, v184
	v_xor_b32_e32 v177, v177, v185
	v_lshl_add_u32 v177, v183, 3, v177
	v_mul_u32_u24_e32 v177, 0x50, v177
	v_add_u32_e32 v178, 6, v184
	v_xor_b32_e32 v178, v178, v185
	v_lshl_add_u32 v178, v183, 3, v178
	v_mul_u32_u24_e32 v178, 0x50, v178
	v_bfe_u32 v0, v0, 5, 1
	s_movk_i32 s4, 0x840
	v_mov_b32_e32 v5, s5
	v_mul_u32_u24_e32 v2, 0x88, v1
	v_lshlrev_b32_e32 v3, 3, v0
	v_mul_u32_u24_e32 v4, 40, v1
	v_mul_u32_u24_e32 v114, 0x840, v0
	v_mad_u32_u24 v0, v0, s4, v5
	v_lshlrev_b32_e32 v5, 7, v27
	v_lshlrev_b32_e32 v115, 2, v1
	v_mov_b32_e32 v48, 0
	s_mov_b32 s3, 0
	v_add3_u32 v116, v0, v5, v115
	s_waitcnt vmcnt(5)
	v_lshlrev_b32_e32 v117, 1, v2
	s_waitcnt vmcnt(4)
	v_lshlrev_b32_e32 v118, 1, v3
	s_waitcnt vmcnt(2)
	v_lshlrev_b32_e32 v119, 1, v4
	v_mov_b32_e32 v49, v48
	v_mov_b32_e32 v50, v48
	v_mov_b32_e32 v51, v48
	v_mov_b32_e32 v52, v48
	v_mov_b32_e32 v53, v48
	v_mov_b32_e32 v54, v48
	v_mov_b32_e32 v55, v48
	v_mov_b32_e32 v56, v48
	v_mov_b32_e32 v57, v48
	v_mov_b32_e32 v58, v48
	v_mov_b32_e32 v59, v48
	v_mov_b32_e32 v60, v48
	v_mov_b32_e32 v61, v48
	v_mov_b32_e32 v62, v48
	v_mov_b32_e32 v63, v48
	v_mov_b32_e32 v32, v48
	v_mov_b32_e32 v33, v48
	v_mov_b32_e32 v34, v48
	v_mov_b32_e32 v35, v48
	v_mov_b32_e32 v36, v48
	v_mov_b32_e32 v37, v48
	v_mov_b32_e32 v38, v48
	v_mov_b32_e32 v39, v48
	v_mov_b32_e32 v40, v48
	v_mov_b32_e32 v41, v48
	v_mov_b32_e32 v42, v48
	v_mov_b32_e32 v43, v48
	v_mov_b32_e32 v44, v48
	v_mov_b32_e32 v45, v48
	v_mov_b32_e32 v46, v48
	v_mov_b32_e32 v47, v48
	v_mov_b32_e32 v16, v48
	v_mov_b32_e32 v17, v48
	v_mov_b32_e32 v18, v48
	v_mov_b32_e32 v19, v48
	v_mov_b32_e32 v20, v48
	v_mov_b32_e32 v21, v48
	v_mov_b32_e32 v22, v48
	v_mov_b32_e32 v23, v48
	v_mov_b32_e32 v24, v48
	v_mov_b32_e32 v25, v48
	v_mov_b32_e32 v26, v48
	v_mov_b32_e32 v27, v48
	v_mov_b32_e32 v28, v48
	v_mov_b32_e32 v29, v48
	v_mov_b32_e32 v30, v48
	v_mov_b32_e32 v31, v48
	v_mov_b32_e32 v0, v48
	v_mov_b32_e32 v1, v48
	v_mov_b32_e32 v2, v48
	v_mov_b32_e32 v3, v48
	v_mov_b32_e32 v4, v48
	v_mov_b32_e32 v5, v48
	v_mov_b32_e32 v6, v48
	v_mov_b32_e32 v7, v48
	v_mov_b32_e32 v8, v48
	v_mov_b32_e32 v9, v48
	v_mov_b32_e32 v10, v48
	v_mov_b32_e32 v11, v48
	v_mov_b32_e32 v12, v48
	v_mov_b32_e32 v13, v48
	v_mov_b32_e32 v14, v48
	v_mov_b32_e32 v15, v48
.LBB0_1833:
	s_and_b32 s4, s3, 1
	s_mul_i32 s5, s4, 0xc210
	s_add_i32 s5, s5, 0
	v_add3_u32 v136, s5, v117, v118
	ds_read_b128 v[64:67], v136
	ds_read_b128 v[96:99], v136 offset:32
	v_cvt_pk_bf16_f32 v80, v48, v49
	v_cvt_pk_bf16_f32 v81, v50, v51
	v_cvt_pk_bf16_f32 v82, v52, v53
	v_cvt_pk_bf16_f32 v83, v54, v55
	ds_read_b128 v[84:87], v136 offset:8704
	ds_read_b128 v[100:103], v136 offset:8736
	s_waitcnt lgkmcnt(3)
	v_mfma_f32_32x32x16_bf16 v[64:79], v[64:67], v[80:83], 0
	v_cvt_pk_bf16_f32 v104, v56, v57
	v_cvt_pk_bf16_f32 v105, v58, v59
	v_cvt_pk_bf16_f32 v106, v60, v61
	v_cvt_pk_bf16_f32 v107, v62, v63
	v_cvt_pk_bf16_f32 v108, v32, v33
	v_cvt_pk_bf16_f32 v109, v34, v35
	v_cvt_pk_bf16_f32 v110, v36, v37
	s_waitcnt vmcnt(0) lgkmcnt(1)
	v_mfma_f32_32x32x16_bf16 v[80:95], v[84:87], v[80:83], 0
	v_cvt_pk_bf16_f32 v111, v38, v39
	v_cvt_pk_bf16_f32 v120, v16, v17
	v_cvt_pk_bf16_f32 v121, v18, v19
	v_cvt_pk_bf16_f32 v122, v20, v21
	v_cvt_pk_bf16_f32 v123, v22, v23
	v_lshl_add_u32 v137, v112, 2, s5
	v_add3_u32 v162, v137, v115, v114
	v_mfma_f32_32x32x16_bf16 v[64:79], v[96:99], v[104:107], v[64:79]
	v_cvt_pk_bf16_f32 v96, v40, v41
	v_cvt_pk_bf16_f32 v97, v42, v43
	v_cvt_pk_bf16_f32 v98, v44, v45
	v_cvt_pk_bf16_f32 v99, v46, v47
	v_mov_b32_e32 v144, s5
	v_add3_u32 v161, s5, v119, v118
	v_add3_u32 v179, s5, v175, v118
	v_add3_u32 v180, s5, v176, v118
	v_add3_u32 v181, s5, v177, v118
	v_add3_u32 v182, s5, v178, v118
	v_add_u32_e32 v163, 0x8000, v162
	s_waitcnt lgkmcnt(0)
	v_mfma_f32_32x32x16_bf16 v[80:95], v[100:103], v[104:107], v[80:95]
	ds_read_b128 v[100:103], v136 offset:64
	ds_read_b128 v[104:107], v136 offset:96
	v_add_u32_e32 v164, 0x8400, v162
	v_add_u32_e32 v165, 0x9000, v162
	v_add_u32_e32 v168, 0x9400, v162
	v_add_u32_e32 v169, 0xa000, v162
	v_add_u32_e32 v170, 0xa400, v162
	v_add_u32_e32 v171, 0xb000, v162
	s_waitcnt lgkmcnt(1)
	v_mfma_f32_32x32x16_bf16 v[64:79], v[100:103], v[108:111], v[64:79]
	ds_read_b128 v[100:103], v136 offset:8768
	ds_read_b128 v[124:127], v136 offset:8800
	v_add_u32_e32 v172, 0xb400, v162
	s_mulk_i32 s4, 0x4200
	s_add_i32 s3, s3, 1
	s_cmp_lg_u32 s3, 64
	s_waitcnt lgkmcnt(1)
	v_mfma_f32_32x32x16_bf16 v[80:95], v[100:103], v[108:111], v[80:95]
	v_cvt_pk_bf16_f32 v100, v24, v25
	v_cvt_pk_bf16_f32 v101, v26, v27
	v_cvt_pk_bf16_f32 v102, v28, v29
	v_cvt_pk_bf16_f32 v103, v30, v31
	v_cvt_pk_bf16_f32 v108, v8, v9
	v_cvt_pk_bf16_f32 v109, v10, v11
	v_cvt_pk_bf16_f32 v110, v12, v13
	v_mfma_f32_32x32x16_bf16 v[64:79], v[104:107], v[96:99], v[64:79]
	v_cvt_pk_bf16_f32 v104, v0, v1
	v_cvt_pk_bf16_f32 v105, v2, v3
	v_cvt_pk_bf16_f32 v106, v4, v5
	v_cvt_pk_bf16_f32 v107, v6, v7
	v_cvt_pk_bf16_f32 v111, v14, v15
	s_waitcnt lgkmcnt(0)
	v_mfma_f32_32x32x16_bf16 v[80:95], v[124:127], v[96:99], v[80:95]
	ds_read_b128 v[96:99], v136 offset:128
	ds_read_b128 v[124:127], v136 offset:160
	s_waitcnt lgkmcnt(1)
; #define LAS __attribute__((address_space(3)))
; #define DR_BAR() do { asm volatile("s_waitcnt lgkmcnt(0)" ::: "memory"); __builtin_amdgcn_s_barrier(); asm volatile("" ::: "memory"); } while (0)
; __device__ __forceinline__ void delta_rec_task(const Params& P, LAS unsigned char* lds, int b, int h, int tid) {
;     ...
;             const LAS float* VB = (const LAS float*)(buf + DR_VB) + 32 * vb + n;
;             float Y[16];
; #pragma unroll
;             for (int r = 0; r < 16; ++r) Y[r] = VB[((r & 3) + 8 * (r >> 2) + 4 * hh) * 132] - X1[r];
;             const bf16x8 YB0 = pack8(Y[0], Y[1], Y[2], Y[3], Y[4], Y[5], Y[6], Y[7]), YB1 = pack8(Y[8], Y[9], Y[10], Y[11], Y[12], Y[13], Y[14], Y[15]);
;             f32x16 VN;
; #pragma unroll
;             for (int r = 0; r < 16; ++r) VN[r] = 0.f;
;             const LAS bf16* TI = (const LAS bf16*)(buf + DR_TI) + n * 40 + 8 * hh; const LAS bf16* AT = (const LAS bf16*)(buf + DR_AT) + n * 40 + 8 * hh;
;             VN = __builtin_amdgcn_mfma_f32_32x32x16_bf16(*(const LAS bf16x8*)TI, YB0, VN, 0, 0, 0);
;             VN = __builtin_amdgcn_mfma_f32_32x32x16_bf16(*(const LAS bf16x8*)(TI + 16), YB1, VN, 0, 0, 0);
;             const bf16x8 VB0 = pack8(VN[0], VN[1], VN[2], VN[3], VN[4], VN[5], VN[6], VN[7]), VB1 = pack8(VN[8], VN[9], VN[10], VN[11], VN[12], VN[13], VN[14], VN[15]);
;             P1 = __builtin_amdgcn_mfma_f32_32x32x16_bf16(*(const LAS bf16x8*)AT, VB0, P1, 0, 0, 0);
;             P1 = __builtin_amdgcn_mfma_f32_32x32x16_bf16(*(const LAS bf16x8*)(AT + 16), VB1, P1, 0, 0, 0);
;             const float egl = *(const LAS float*)(buf + DR_EGL);
;             const LAS bf16* KDT = (const LAS bf16*)(buf + DR_KDT) + n * 40 + 8 * hh;
; #pragma unroll
;             for (int kb = 0; kb < 4; ++kb) {
; #pragma unroll
;                 for (int r = 0; r < 16; ++r) S[kb][r] *= egl;
;                 S[kb] = __builtin_amdgcn_mfma_f32_32x32x16_bf16(*(const LAS bf16x8*)(KDT + kb * 32 * 40), VB0, S[kb], 0, 0, 0);
;                 S[kb] = __builtin_amdgcn_mfma_f32_32x32x16_bf16(*(const LAS bf16x8*)(KDT + kb * 32 * 40 + 16), VB1, S[kb], 0, 0, 0); }
;             LAS float* op = (LAS float*)(lds + DR_OB) + (c & 1) * 32 * 132 + 4 * hh * 132 + 32 * vb + n;
; #pragma unroll
;             for (int r = 0; r < 16; ++r) op[((r & 3) + 8 * (r >> 2)) * 132] = P1[r];
;             DR_BAR();
;         }
	v_mfma_f32_32x32x16_bf16 v[64:79], v[96:99], v[120:123], v[64:79]
	ds_read_b128 v[96:99], v136 offset:8832
	ds_read_b128 v[128:131], v136 offset:8864
	s_waitcnt lgkmcnt(2)
	v_mfma_f32_32x32x16_bf16 v[64:79], v[124:127], v[100:103], v[64:79]
	s_waitcnt lgkmcnt(1)
	v_mfma_f32_32x32x16_bf16 v[80:95], v[96:99], v[120:123], v[80:95]
	ds_read_b128 v[96:99], v136 offset:8896
	ds_read_b128 v[120:123], v136 offset:192
	ds_read_b128 v[132:135], v136 offset:224
	ds_read_b128 v[124:127], v136 offset:8928
	ds_read_b128 v[136:139], v161 offset:27680
	ds_read_b128 v[140:143], v161 offset:30208
	ds_read_b32 v160, v144 offset:49664
	ds_read_b128 v[144:147], v179 offset:17408
	ds_read_b128 v[148:151], v180 offset:17408
	s_waitcnt lgkmcnt(2)
	v_pk_mul_f32 v[62:63], v[62:63], v[160:161] op_sel_hi:[1,0]
	v_pk_mul_f32 v[60:61], v[60:61], v[160:161] op_sel_hi:[1,0]
	v_mfma_f32_32x32x16_bf16 v[64:79], v[120:123], v[104:107], v[64:79]
	v_mul_f32_e64 v58, v58, v160
	v_mul_f32_e64 v59, v59, v160
	v_mul_f32_e64 v56, v56, v160
	v_mul_f32_e64 v57, v57, v160
	v_mul_f32_e64 v54, v54, v160
	v_mul_f32_e64 v55, v55, v160
	v_pk_mul_f32 v[52:53], v[52:53], v[160:161] op_sel_hi:[1,0]
	v_pk_mul_f32 v[50:51], v[50:51], v[160:161] op_sel_hi:[1,0]
	v_pk_mul_f32 v[48:49], v[48:49], v[160:161] op_sel_hi:[1,0]
	v_pk_mul_f32 v[46:47], v[46:47], v[160:161] op_sel_hi:[1,0]
	v_mfma_f32_32x32x16_bf16 v[80:95], v[128:131], v[100:103], v[80:95]
	ds_read_b128 v[128:131], v181 offset:17408
	ds_read_b128 v[152:155], v182 offset:17408
	ds_read_b128 v[100:103], v161 offset:27648
	ds_read_b128 v[156:159], v182 offset:17440
	ds_read2_b32 v[120:121], v163 offset1:132
	ds_read2_b32 v[122:123], v164 offset0:8 offset1:140
	v_pk_mul_f32 v[44:45], v[44:45], v[160:161] op_sel_hi:[1,0]
	v_pk_mul_f32 v[42:43], v[42:43], v[160:161] op_sel_hi:[1,0]
	v_pk_mul_f32 v[40:41], v[40:41], v[160:161] op_sel_hi:[1,0]
	v_pk_mul_f32 v[38:39], v[38:39], v[160:161] op_sel_hi:[1,0]
	v_pk_mul_f32 v[36:37], v[36:37], v[160:161] op_sel_hi:[1,0]
	v_mfma_f32_32x32x16_bf16 v[64:79], v[132:135], v[108:111], v[64:79]
	v_mul_f32_e64 v34, v34, v160
	v_mul_f32_e64 v35, v35, v160
	v_mul_f32_e64 v32, v32, v160
	v_mul_f32_e64 v33, v33, v160
	v_mul_f32_e64 v30, v30, v160
	v_mul_f32_e64 v31, v31, v160
	v_pk_mul_f32 v[28:29], v[28:29], v[160:161] op_sel_hi:[1,0]
	v_pk_mul_f32 v[26:27], v[26:27], v[160:161] op_sel_hi:[1,0]
	v_pk_mul_f32 v[24:25], v[24:25], v[160:161] op_sel_hi:[1,0]
	v_pk_mul_f32 v[22:23], v[22:23], v[160:161] op_sel_hi:[1,0]
	v_mfma_f32_32x32x16_bf16 v[80:95], v[96:99], v[104:107], v[80:95]
	ds_read2_b32 v[96:97], v165 offset0:32 offset1:164
	ds_read2_b32 v[98:99], v168 offset0:40 offset1:172
	ds_read2_b32 v[104:105], v169 offset0:64 offset1:196
	ds_read2_b32 v[162:163], v170 offset0:72 offset1:204
	ds_read2_b32 v[164:165], v171 offset0:96 offset1:228
	ds_read2_b32 v[168:169], v172 offset0:104 offset1:236
	s_waitcnt lgkmcnt(7)
	v_pk_add_f32 v[64:65], v[120:121], v[64:65] neg_lo:[0,1] neg_hi:[0,1]
	s_waitcnt lgkmcnt(6)
	v_pk_add_f32 v[66:67], v[122:123], v[66:67] neg_lo:[0,1] neg_hi:[0,1]
	s_waitcnt lgkmcnt(5)
	v_pk_add_f32 v[68:69], v[96:97], v[68:69] neg_lo:[0,1] neg_hi:[0,1]
	s_waitcnt lgkmcnt(4)
	v_pk_add_f32 v[70:71], v[98:99], v[70:71] neg_lo:[0,1] neg_hi:[0,1]
	v_cvt_pk_bf16_f32 v64, v64, v65
	v_cvt_pk_bf16_f32 v65, v66, v67
	v_cvt_pk_bf16_f32 v66, v68, v69
	v_cvt_pk_bf16_f32 v67, v70, v71
	v_mfma_f32_32x32x16_bf16 v[80:95], v[124:127], v[108:111], v[80:95]
	s_waitcnt lgkmcnt(3)
	v_add_f32_e64 v72, v104, -v72
	v_add_f32_e64 v73, v105, -v73
	s_waitcnt lgkmcnt(1)
	v_add_f32_e64 v68, v164, -v76
	v_add_f32_e64 v69, v165, -v77
	s_waitcnt lgkmcnt(0)
	v_pk_add_f32 v[70:71], v[168:169], v[78:79] neg_lo:[0,1] neg_hi:[0,1]
	v_pk_mul_f32 v[20:21], v[20:21], v[160:161] op_sel_hi:[1,0]
	v_pk_mul_f32 v[18:19], v[18:19], v[160:161] op_sel_hi:[1,0]
	v_pk_mul_f32 v[16:17], v[16:17], v[160:161] op_sel_hi:[1,0]
	v_pk_mul_f32 v[14:15], v[14:15], v[160:161] op_sel_hi:[1,0]
	v_mfma_f32_32x32x16_bf16 v[96:111], v[100:103], v[64:67], 0
	v_add_f32_e64 v66, v162, -v74
	v_add_f32_e64 v67, v163, -v75
	v_cvt_pk_bf16_f32 v64, v72, v73
	v_cvt_pk_bf16_f32 v65, v66, v67
	v_cvt_pk_bf16_f32 v66, v68, v69
	v_cvt_pk_bf16_f32 v67, v70, v71
	v_pk_mul_f32 v[12:13], v[12:13], v[160:161] op_sel_hi:[1,0]
	v_pk_mul_f32 v[10:11], v[10:11], v[160:161] op_sel_hi:[1,0]
	v_mfma_f32_32x32x16_bf16 v[96:111], v[136:139], v[64:67], v[96:111]
	v_mul_f32_e64 v8, v8, v160
	v_mul_f32_e64 v9, v9, v160
	v_mul_f32_e64 v6, v6, v160
	v_mul_f32_e64 v7, v7, v160
	v_mul_f32_e64 v4, v4, v160
	v_mul_f32_e64 v5, v5, v160
	v_pk_mul_f32 v[2:3], v[2:3], v[160:161] op_sel_hi:[1,0]
	v_pk_mul_f32 v[0:1], v[0:1], v[160:161] op_sel_hi:[1,0]
	v_add_u32_e32 v72, s4, v116
	v_add_u32_e32 v73, 0x400, v72
	s_nop 1
	v_cvt_pk_bf16_f32 v64, v96, v97
	v_cvt_pk_bf16_f32 v65, v98, v99
	v_cvt_pk_bf16_f32 v66, v100, v101
	v_cvt_pk_bf16_f32 v67, v102, v103
	v_cvt_pk_bf16_f32 v68, v104, v105
	v_cvt_pk_bf16_f32 v69, v106, v107
	v_mfma_f32_32x32x16_bf16 v[48:63], v[144:147], v[64:67], v[48:63]
	v_cvt_pk_bf16_f32 v70, v108, v109
	v_cvt_pk_bf16_f32 v71, v110, v111
	v_add_u32_e32 v74, 0x1000, v72
	v_add_u32_e32 v75, 0x1400, v72
	v_add_u32_e32 v76, 0x2000, v72
	v_add_u32_e32 v77, 0x2400, v72
	v_add_u32_e32 v78, 0x3000, v72
	v_mfma_f32_32x32x16_bf16 v[32:47], v[148:151], v[64:67], v[32:47]
	v_add_u32_e32 v79, 0x3400, v72
	v_mfma_f32_32x32x16_bf16 v[16:31], v[128:131], v[64:67], v[16:31]
	v_mfma_f32_32x32x16_bf16 v[0:15], v[152:155], v[64:67], v[0:15]
	v_mfma_f32_32x32x16_bf16 v[80:95], v[140:143], v[64:67], v[80:95]
	ds_read_b128 v[64:67], v179 offset:17440
	s_waitcnt lgkmcnt(0)
	v_mfma_f32_32x32x16_bf16 v[48:63], v[64:67], v[68:71], v[48:63]
	ds_read_b128 v[64:67], v180 offset:17440
	s_waitcnt lgkmcnt(0)
	v_mfma_f32_32x32x16_bf16 v[32:47], v[64:67], v[68:71], v[32:47]
	ds_read_b128 v[64:67], v181 offset:17440
	s_waitcnt lgkmcnt(0)
	v_mfma_f32_32x32x16_bf16 v[16:31], v[64:67], v[68:71], v[16:31]
	ds_read_b128 v[64:67], v161 offset:30240
	s_waitcnt lgkmcnt(0)
	v_mfma_f32_32x32x16_bf16 v[80:95], v[64:67], v[68:71], v[80:95]
	s_nop 11
	ds_write2_b32 v72, v80, v81 offset1:132
	ds_write2_b32 v73, v82, v83 offset0:8 offset1:140
	ds_write2_b32 v74, v84, v85 offset0:32 offset1:164
	ds_write2_b32 v75, v86, v87 offset0:40 offset1:172
	ds_write2_b32 v76, v88, v89 offset0:64 offset1:196
	ds_write2_b32 v77, v90, v91 offset0:72 offset1:204
	ds_write2_b32 v78, v92, v93 offset0:96 offset1:228
	ds_write2_b32 v79, v94, v95 offset0:104 offset1:236
	v_mfma_f32_32x32x16_bf16 v[0:15], v[156:159], v[68:71], v[0:15]
	s_waitcnt lgkmcnt(0)
	s_barrier
	s_cbranch_scc1 .LBB0_1833
	s_andn2_saveexec_b64 s[6:7], s[6:7]
	s_cbranch_execz .LBB0_1818

; #define LAS __attribute__((address_space(3)))
; __device__ __forceinline__ unsigned f2bf(float f) { return pk2(f, f) & 0xffffu; }
; __device__ __forceinline__ void unpack8(const u32x4 u, float* x) { x[0] = bflo(u.x); x[1] = bfhi(u.x); x[2] = bflo(u.y); x[3] = bfhi(u.y); x[4] = bflo(u.z); x[5] = bfhi(u.z); x[6] = bflo(u.w); x[7] = bfhi(u.w); }
; __device__ __forceinline__ int perm16(int e) { return (e & ~12) | ((e >> 1) & 4) | ((e << 1) & 8); }
; __device__ __forceinline__ void delta_rec_stage(LAS unsigned char* buf, int pt, const DeltaPre& dp) {
;     const int tt = pt >> 3, dg = pt & 7, d0 = dg * 16;
;     { LAS bf16* dst = (LAS bf16*)(buf + (pt < 128 ? DR_TI : DR_AT)) + ((pt & 127) >> 2) * 40 + (pt & 3) * 8; *(LAS u32x4*)dst = dp.tia; }
;     if (pt == 0) *(LAS float*)(buf + DR_EGL) = __expf(dp.gl);
;     const float eg = __expf(dp.gct), ekd = __expf(dp.gl - dp.gct);
;     const float fq = dp.nq * eg, fkb = dp.nk * dp.bet * eg, fkd = dp.nk * ekd, bet = dp.bet;
;     float k[16], q[16], v[16];
;     unpack8(dp.k0, k); unpack8(dp.k1, k + 8); unpack8(dp.q0, q); unpack8(dp.q1, q + 8); unpack8(dp.v0, v); unpack8(dp.v1, v + 8);
;     LAS bf16* KB = (LAS bf16*)(buf + DR_KB) + tt * 136 + d0; LAS bf16* QD = (LAS bf16*)(buf + DR_QD) + tt * 136 + d0;
;     *(LAS bf16x8*)KB = pack8(k[0] * fkb, k[1] * fkb, k[2] * fkb, k[3] * fkb, k[8] * fkb, k[9] * fkb, k[10] * fkb, k[11] * fkb);
;     *(LAS bf16x8*)(KB + 8) = pack8(k[4] * fkb, k[5] * fkb, k[6] * fkb, k[7] * fkb, k[12] * fkb, k[13] * fkb, k[14] * fkb, k[15] * fkb);
;     *(LAS bf16x8*)QD = pack8(q[0] * fq, q[1] * fq, q[2] * fq, q[3] * fq, q[8] * fq, q[9] * fq, q[10] * fq, q[11] * fq);
;     *(LAS bf16x8*)(QD + 8) = pack8(q[4] * fq, q[5] * fq, q[6] * fq, q[7] * fq, q[12] * fq, q[13] * fq, q[14] * fq, q[15] * fq);
;     LAS bf16* KDT = (LAS bf16*)(buf + DR_KDT) + d0 * 40 + perm16(tt);
; #pragma unroll
;     for (int e = 0; e < 16; ++e) KDT[e * 40] = (bf16)f2bf(k[e] * fkd);
;     LAS float* VB = (LAS float*)(buf + DR_VB) + tt * 132 + d0;
; #pragma unroll
;     for (int e4 = 0; e4 < 4; ++e4) *(LAS f32x4*)(VB + 4 * e4) = (f32x4){v[4 * e4] * bet, v[4 * e4 + 1] * bet, v[4 * e4 + 2] * bet, v[4 * e4 + 3] * bet};
; }
.LBB0_1837:
	s_or_b64 exec, exec, s[18:19]
	v_lshrrev_b32_e32 v33, 1, v22
	v_and_b32_e32 v128, 4, v33
	v_lshlrev_b32_e32 v33, 1, v22
	v_and_b32_e32 v129, 8, v33
	v_mul_f32_e32 v33, 0x3fb8aa3b, v117
	v_sub_f32_e32 v34, v118, v117
	v_exp_f32_e32 v33, v33
	v_mul_f32_e32 v34, 0x3fb8aa3b, v34
	v_exp_f32_e32 v34, v34
	s_movk_i32 s18, 0x88
	v_mul_f32_e32 v35, v119, v110
	v_mul_lo_u32 v32, v22, s18
	v_mul_f32_e32 v42, v35, v33
	v_lshlrev_b32_e32 v52, 16, v84
	v_and_b32_e32 v53, 0xffff0000, v84
	v_lshlrev_b32_e32 v54, 16, v85
	v_and_b32_e32 v55, 0xffff0000, v85
	v_lshlrev_b32_e32 v56, 16, v80
	v_and_b32_e32 v57, 0xffff0000, v80
	v_lshlrev_b32_e32 v60, 16, v81
	v_and_b32_e32 v61, 0xffff0000, v81
	v_mul_f32_e32 v40, v120, v33
	v_mul_f32_e32 v117, v119, v34
	v_lshlrev_b32_e32 v91, 1, v32
	v_pk_mul_f32 v[32:33], v[42:43], v[52:53] op_sel_hi:[0,1]
	v_pk_mul_f32 v[34:35], v[42:43], v[54:55] op_sel_hi:[0,1]
	v_pk_mul_f32 v[58:59], v[42:43], v[56:57] op_sel_hi:[0,1]
	v_pk_mul_f32 v[62:63], v[42:43], v[60:61] op_sel_hi:[0,1]
	v_add3_u32 v118, 0, v91, v114
	v_cvt_pk_bf16_f32 v32, v32, v33
	v_cvt_pk_bf16_f32 v33, v34, v35
	v_cvt_pk_bf16_f32 v34, v58, v59
	v_cvt_pk_bf16_f32 v35, v62, v63
	v_lshlrev_b32_e32 v58, 16, v86
	v_and_b32_e32 v59, 0xffff0000, v86
	v_lshlrev_b32_e32 v62, 16, v87
	v_and_b32_e32 v63, 0xffff0000, v87
	v_lshlrev_b32_e32 v84, 16, v82
	v_and_b32_e32 v85, 0xffff0000, v82
	v_lshlrev_b32_e32 v86, 16, v83
	v_and_b32_e32 v87, 0xffff0000, v83
	ds_write_b128 v118, v[32:35] offset:49680
	v_pk_mul_f32 v[32:33], v[42:43], v[58:59] op_sel_hi:[0,1]
	v_pk_mul_f32 v[34:35], v[42:43], v[62:63] op_sel_hi:[0,1]
	v_pk_mul_f32 v[80:81], v[42:43], v[84:85] op_sel_hi:[0,1]
	v_pk_mul_f32 v[42:43], v[42:43], v[86:87] op_sel_hi:[0,1]
	v_cvt_pk_bf16_f32 v32, v32, v33
	v_cvt_pk_bf16_f32 v33, v34, v35
	v_cvt_pk_bf16_f32 v34, v80, v81
	v_cvt_pk_bf16_f32 v35, v42, v43
	ds_write_b128 v118, v[32:35] offset:49696
	v_lshlrev_b32_e32 v32, 16, v76
	v_and_b32_e32 v33, 0xffff0000, v76
	v_lshlrev_b32_e32 v34, 16, v77
	v_and_b32_e32 v35, 0xffff0000, v77
	v_lshlrev_b32_e32 v42, 16, v72
	v_and_b32_e32 v43, 0xffff0000, v72
	v_lshlrev_b32_e32 v72, 16, v73
	v_and_b32_e32 v73, 0xffff0000, v73
	v_pk_mul_f32 v[32:33], v[40:41], v[32:33] op_sel_hi:[0,1]
	v_pk_mul_f32 v[34:35], v[40:41], v[34:35] op_sel_hi:[0,1]
	v_pk_mul_f32 v[42:43], v[40:41], v[42:43] op_sel_hi:[0,1]
	v_pk_mul_f32 v[72:73], v[40:41], v[72:73] op_sel_hi:[0,1]
	v_cvt_pk_bf16_f32 v32, v32, v33
	v_cvt_pk_bf16_f32 v33, v34, v35
	v_cvt_pk_bf16_f32 v34, v42, v43
	v_cvt_pk_bf16_f32 v35, v72, v73
	s_movk_i32 s18, 0x210
	ds_write_b128 v118, v[32:35] offset:58384
	v_lshlrev_b32_e32 v32, 16, v78
	v_and_b32_e32 v33, 0xffff0000, v78
	v_lshlrev_b32_e32 v34, 16, v79
	v_and_b32_e32 v35, 0xffff0000, v79
	v_lshlrev_b32_e32 v42, 16, v74
	v_and_b32_e32 v43, 0xffff0000, v74
	v_lshlrev_b32_e32 v72, 16, v75
	v_and_b32_e32 v73, 0xffff0000, v75
	v_mul_lo_u32 v88, v22, s18
	s_add_i32 s18, 0, 0x18420
	v_pk_mul_f32 v[32:33], v[40:41], v[32:33] op_sel_hi:[0,1]
	v_pk_mul_f32 v[34:35], v[40:41], v[34:35] op_sel_hi:[0,1]
	v_pk_mul_f32 v[42:43], v[40:41], v[42:43] op_sel_hi:[0,1]
	v_pk_mul_f32 v[40:41], v[40:41], v[72:73] op_sel_hi:[0,1]
	v_mov_b32_e32 v90, 0
	v_and_b32_e32 v127, -13, v22
	v_add3_u32 v89, s18, v88, v111
	v_cvt_pk_bf16_f32 v32, v32, v33
	v_cvt_pk_bf16_f32 v33, v34, v35
	v_cvt_pk_bf16_f32 v34, v42, v43
	v_cvt_pk_bf16_f32 v35, v40, v41
	s_add_i32 s18, 0, 0x10610
	v_lshlrev_b32_e32 v80, 1, v128
	ds_write_b128 v118, v[32:35] offset:58400
	v_add3_u32 v32, s18, v90, v80
	v_lshlrev_b32_e32 v81, 1, v127
	v_lshlrev_b32_e32 v82, 1, v129
	v_mul_f32_e32 v33, v117, v52
	v_add3_u32 v32, v32, v81, v82
	v_cvt_pk_bf16_f32 v33, v33, s0
	v_add_u32_e32 v230, v32, v222
	v_add_u32_e32 v231, v32, v223
	v_add_u32_e32 v232, v32, v224
	v_add_u32_e32 v233, v32, v225
	v_add_u32_e32 v234, v32, v226
	v_add_u32_e32 v235, v32, v227
	v_add_u32_e32 v236, v32, v228
	v_add_u32_e32 v237, v32, v229
	ds_write_b16 v230, v33
	v_mul_f32_e32 v33, v117, v53
	v_cvt_pk_bf16_f32 v33, v33, s0
	ds_write_b16 v231, v33 offset:640
	v_mul_f32_e32 v33, v117, v54
	v_cvt_pk_bf16_f32 v33, v33, s0
	ds_write_b16 v232, v33 offset:1280
	v_mul_f32_e32 v33, v117, v55
	v_cvt_pk_bf16_f32 v33, v33, s0
	ds_write_b16 v233, v33 offset:1920
	v_mul_f32_e32 v33, v117, v58
	v_cvt_pk_bf16_f32 v33, v33, s0
	ds_write_b16 v234, v33 offset:2560
	v_mul_f32_e32 v33, v117, v59
	v_cvt_pk_bf16_f32 v33, v33, s0
	ds_write_b16 v235, v33 offset:3200
	v_mul_f32_e32 v33, v117, v62
	v_cvt_pk_bf16_f32 v33, v33, s0
	ds_write_b16 v236, v33 offset:3840
	v_mul_f32_e32 v33, v117, v63
	v_cvt_pk_bf16_f32 v33, v33, s0
	ds_write_b16 v237, v33 offset:4480
	v_mul_f32_e32 v33, v117, v56
	v_cvt_pk_bf16_f32 v33, v33, s0
	ds_write_b16 v230, v33 offset:5120
	v_mul_f32_e32 v33, v117, v57
	v_cvt_pk_bf16_f32 v33, v33, s0
	ds_write_b16 v231, v33 offset:5760
	v_mul_f32_e32 v33, v117, v60
	v_cvt_pk_bf16_f32 v33, v33, s0
	ds_write_b16 v232, v33 offset:6400
	v_mul_f32_e32 v33, v117, v61
	v_cvt_pk_bf16_f32 v33, v33, s0
	ds_write_b16 v233, v33 offset:7040
	v_mul_f32_e32 v33, v117, v84
	v_cvt_pk_bf16_f32 v33, v33, s0
	ds_write_b16 v234, v33 offset:7680
	v_mul_f32_e32 v33, v117, v85
	v_cvt_pk_bf16_f32 v33, v33, s0
	ds_write_b16 v235, v33 offset:8320
	v_mul_f32_e32 v33, v117, v86
	v_cvt_pk_bf16_f32 v33, v33, s0
	ds_write_b16 v236, v33 offset:8960
	v_mul_f32_e32 v33, v117, v87
	v_cvt_pk_bf16_f32 v33, v33, s0
	ds_write_b16 v237, v33 offset:9600
	s_add_i32 s18, 0, 0x14210
	v_lshlrev_b32_e32 v32, 16, v68
	v_and_b32_e32 v33, 0xffff0000, v68
	v_lshlrev_b32_e32 v34, 16, v69
	v_and_b32_e32 v35, 0xffff0000, v69
	v_add3_u32 v40, s18, v88, v111
	v_pk_mul_f32 v[32:33], v[110:111], v[32:33] op_sel_hi:[0,1]
	v_pk_mul_f32 v[34:35], v[110:111], v[34:35] op_sel_hi:[0,1]
	ds_write_b128 v40, v[32:35]
	v_lshlrev_b32_e32 v32, 16, v70
	v_and_b32_e32 v33, 0xffff0000, v70
	v_lshlrev_b32_e32 v34, 16, v71
	v_and_b32_e32 v35, 0xffff0000, v71
	v_pk_mul_f32 v[32:33], v[110:111], v[32:33] op_sel_hi:[0,1]
	v_pk_mul_f32 v[34:35], v[110:111], v[34:35] op_sel_hi:[0,1]
	ds_write_b128 v40, v[32:35] offset:16
	v_lshlrev_b32_e32 v32, 16, v64
	v_and_b32_e32 v33, 0xffff0000, v64
	v_lshlrev_b32_e32 v34, 16, v65
	v_and_b32_e32 v35, 0xffff0000, v65
	v_pk_mul_f32 v[32:33], v[110:111], v[32:33] op_sel_hi:[0,1]
	v_pk_mul_f32 v[34:35], v[110:111], v[34:35] op_sel_hi:[0,1]
	ds_write_b128 v40, v[32:35] offset:32
	v_lshlrev_b32_e32 v32, 16, v66
	v_and_b32_e32 v33, 0xffff0000, v66
	v_lshlrev_b32_e32 v34, 16, v67
	v_and_b32_e32 v35, 0xffff0000, v67
	v_pk_mul_f32 v[32:33], v[110:111], v[32:33] op_sel_hi:[0,1]
	v_pk_mul_f32 v[34:35], v[110:111], v[34:35] op_sel_hi:[0,1]
	ds_write_b128 v40, v[32:35] offset:48
	v_lshl_add_u64 v[32:33], v[20:21], 0, s[12:13]
	v_and_b32_e32 v20, 0x7f, v26
	v_lshlrev_b32_e32 v20, 4, v20
	v_lshl_add_u64 v[32:33], v[32:33], 0, v[20:21]
	v_lshl_add_u64 v[24:25], s[4:5], 0, v[24:25]
	v_add_lshl_u32 v20, s20, v27, 1
	v_lshl_add_u64 v[72:73], v[24:25], 0, v[20:21]
	v_and_b32_e32 v20, 7, v26
	s_waitcnt lgkmcnt(0)
	s_barrier
; __device__ __forceinline__ unsigned char* karg_ws() { return *(volatile KAS ucptr_t*)((const KAS char*)__builtin_amdgcn_kernarg_segment_ptr() + 264); }
; __device__ __forceinline__ void delta_rec_task(const Params& P, LAS unsigned char* lds, int b, int h, int tid) {
;     ...
;         bf16* zgp = (bf16*)(karg_ws() + WS_Z + 5 * ZB) + ((size_t)b * SEQ + (pt >> 3)) * D + h * 128 + (pt & 7) * 16;
;         u32x4 zc0 = {0u, 0u, 0u, 0u}, zc1 = zc0, zn0, zn1;
;     ...
;         for (int c = 0; c < NC; ++c) {
;             if (c > 0) { dcur = dnxt; zc0 = zn0; zc1 = zn1; }
;             if (c + 2 < NC) delta_pre_load(b, h, c + 2, pt, dnxt);
;             zn0 = *(const u32x4*)(zgp + (size_t)c * 32 * D); zn1 = *(const u32x4*)(zgp + (size_t)c * 32 * D + 8);
	v_lshlrev_b64 v[74:75], 2, v[22:23]
	v_lshl_add_u64 v[22:23], v[24:25], 0, s[14:15]
	v_lshlrev_b32_e32 v20, 5, v20
	s_mov_b64 s[12:13], 0x1800
	v_lshl_add_u64 v[20:21], v[22:23], 0, v[20:21]
	v_lshl_add_u64 v[70:71], v[32:33], 0, s[12:13]
	s_lshl_b64 s[4:5], s[2:3], 13
	v_lshl_add_u64 v[76:77], s[16:17], 0, v[20:21]
	s_mov_b64 s[12:13], 0
	s_mov_b64 s[16:17], 0xb130000
	s_mov_b64 s[18:19], 0x3030000
	s_mov_b64 s[20:21], 0xd170000
	s_mov_b32 s3, 0xb130000
	s_mov_b32 s14, 0x3030000
	s_mov_b32 s34, 0xd170000
	s_mov_b32 s35, 0x2880000
	v_mov_b32_e32 v69, 0x2880000
	s_mov_b64 s[22:23], 0xf190000
	v_mov_b32_e32 v83, 0x358637bd
	s_mov_b64 s[24:25], 0x800
	s_mov_b32 s36, s15

; #define LAS __attribute__((address_space(3)))
; __device__ __forceinline__ unsigned f2bf(float f) { return pk2(f, f) & 0xffffu; }
; __device__ __forceinline__ int perm16(int e) { return (e & ~12) | ((e >> 1) & 4) | ((e << 1) & 8); }
; __device__ __forceinline__ void delta_rec_stage(LAS unsigned char* buf, int pt, const DeltaPre& dp) {
;     const int tt = pt >> 3, dg = pt & 7, d0 = dg * 16;
;     { LAS bf16* dst = (LAS bf16*)(buf + (pt < 128 ? DR_TI : DR_AT)) + ((pt & 127) >> 2) * 40 + (pt & 3) * 8; *(LAS u32x4*)dst = dp.tia; }
;     if (pt == 0) *(LAS float*)(buf + DR_EGL) = __expf(dp.gl);
;     const float eg = __expf(dp.gct), ekd = __expf(dp.gl - dp.gct);
;     const float fq = dp.nq * eg, fkb = dp.nk * dp.bet * eg, fkd = dp.nk * ekd, bet = dp.bet;
;     float k[16], q[16], v[16];
;     unpack8(dp.k0, k); unpack8(dp.k1, k + 8); unpack8(dp.q0, q); unpack8(dp.q1, q + 8); unpack8(dp.v0, v); unpack8(dp.v1, v + 8);
;     LAS bf16* KB = (LAS bf16*)(buf + DR_KB) + tt * 136 + d0; LAS bf16* QD = (LAS bf16*)(buf + DR_QD) + tt * 136 + d0;
;     *(LAS bf16x8*)KB = pack8(k[0] * fkb, k[1] * fkb, k[2] * fkb, k[3] * fkb, k[8] * fkb, k[9] * fkb, k[10] * fkb, k[11] * fkb);
;     *(LAS bf16x8*)(KB + 8) = pack8(k[4] * fkb, k[5] * fkb, k[6] * fkb, k[7] * fkb, k[12] * fkb, k[13] * fkb, k[14] * fkb, k[15] * fkb);
;     *(LAS bf16x8*)QD = pack8(q[0] * fq, q[1] * fq, q[2] * fq, q[3] * fq, q[8] * fq, q[9] * fq, q[10] * fq, q[11] * fq);
;     *(LAS bf16x8*)(QD + 8) = pack8(q[4] * fq, q[5] * fq, q[6] * fq, q[7] * fq, q[12] * fq, q[13] * fq, q[14] * fq, q[15] * fq);
;     LAS bf16* KDT = (LAS bf16*)(buf + DR_KDT) + d0 * 40 + perm16(tt);
; #pragma unroll
;     for (int e = 0; e < 16; ++e) KDT[e * 40] = (bf16)f2bf(k[e] * fkd);
;     LAS float* VB = (LAS float*)(buf + DR_VB) + tt * 132 + d0;
; #pragma unroll
;     for (int e4 = 0; e4 < 4; ++e4) *(LAS f32x4*)(VB + 4 * e4) = (f32x4){v[4 * e4] * bet, v[4 * e4 + 1] * bet, v[4 * e4 + 2] * bet, v[4 * e4 + 3] * bet};
; }
; __device__ __forceinline__ void delta_out_norm(const LAS float* ob, int pt, const float* dn16, const u32x4 z0, const u32x4 z1, bf16* dst) {
;     const LAS float* p = ob + (pt >> 3) * 132 + (pt & 7) * 16;
;     float o[16], z[16];
; #pragma unroll
;     for (int e4 = 0; e4 < 4; ++e4) { const f32x4 t = *(const LAS f32x4*)(p + 4 * e4); o[4 * e4] = t[0]; o[4 * e4 + 1] = t[1]; o[4 * e4 + 2] = t[2]; o[4 * e4 + 3] = t[3]; }
.LBB0_1840:
	s_or_b64 exec, exec, s[26:27]
	v_mul_f32_e32 v110, 0x3fb8aa3b, v123
	v_exp_f32_e32 v117, v110
	v_sub_f32_e32 v110, v124, v123
	v_mul_f32_e32 v110, 0x3fb8aa3b, v110
	v_exp_f32_e32 v119, v110
	v_mul_f32_e32 v118, v116, v125
	v_mul_f32_e32 v118, v117, v118
	v_lshlrev_b32_e32 v128, 16, v48
	v_and_b32_e32 v129, 0xffff0000, v48
	v_lshlrev_b32_e32 v48, 16, v49
	v_and_b32_e32 v49, 0xffff0000, v49
	v_lshlrev_b32_e32 v130, 16, v44
	v_and_b32_e32 v131, 0xffff0000, v44
	v_lshlrev_b32_e32 v134, 16, v45
	v_and_b32_e32 v135, 0xffff0000, v45
	v_mul_f32_e32 v110, v117, v126
	v_mul_f32_e32 v117, v125, v119
	v_pk_mul_f32 v[124:125], v[118:119], v[128:129] op_sel_hi:[0,1]
	v_pk_mul_f32 v[126:127], v[118:119], v[48:49] op_sel_hi:[0,1]
	v_pk_mul_f32 v[132:133], v[118:119], v[130:131] op_sel_hi:[0,1]
	v_pk_mul_f32 v[44:45], v[118:119], v[134:135] op_sel_hi:[0,1]
	v_add3_u32 v120, s37, v91, v114
	v_cvt_pk_bf16_f32 v124, v124, v125
	v_cvt_pk_bf16_f32 v125, v126, v127
	v_cvt_pk_bf16_f32 v126, v132, v133
	v_cvt_pk_bf16_f32 v127, v44, v45
	ds_write_b128 v120, v[124:127]
	v_lshlrev_b32_e32 v124, 16, v50
	v_and_b32_e32 v125, 0xffff0000, v50
	v_lshlrev_b32_e32 v50, 16, v51
	v_and_b32_e32 v51, 0xffff0000, v51
	v_lshlrev_b32_e32 v132, 16, v46
	v_and_b32_e32 v133, 0xffff0000, v46
	v_lshlrev_b32_e32 v138, 16, v47
	v_and_b32_e32 v139, 0xffff0000, v47
	v_pk_mul_f32 v[44:45], v[118:119], v[124:125] op_sel_hi:[0,1]
	v_pk_mul_f32 v[126:127], v[118:119], v[50:51] op_sel_hi:[0,1]
	v_pk_mul_f32 v[136:137], v[118:119], v[132:133] op_sel_hi:[0,1]
	v_pk_mul_f32 v[118:119], v[118:119], v[138:139] op_sel_hi:[0,1]
	v_cvt_pk_bf16_f32 v44, v44, v45
	v_cvt_pk_bf16_f32 v45, v126, v127
	v_cvt_pk_bf16_f32 v46, v136, v137
	v_cvt_pk_bf16_f32 v47, v118, v119
	ds_write_b128 v120, v[44:47] offset:16
	v_lshlrev_b32_e32 v44, 16, v36
	v_and_b32_e32 v45, 0xffff0000, v36
	v_lshlrev_b32_e32 v36, 16, v37
	v_and_b32_e32 v37, 0xffff0000, v37
	v_lshlrev_b32_e32 v46, 16, v28
	v_and_b32_e32 v47, 0xffff0000, v28
	v_lshlrev_b32_e32 v28, 16, v29
	v_and_b32_e32 v29, 0xffff0000, v29
	v_pk_mul_f32 v[44:45], v[110:111], v[44:45] op_sel_hi:[0,1]
	v_pk_mul_f32 v[36:37], v[110:111], v[36:37] op_sel_hi:[0,1]
	v_pk_mul_f32 v[46:47], v[110:111], v[46:47] op_sel_hi:[0,1]
	v_pk_mul_f32 v[28:29], v[110:111], v[28:29] op_sel_hi:[0,1]
	v_cvt_pk_bf16_f32 v44, v44, v45
	v_cvt_pk_bf16_f32 v45, v36, v37
	v_cvt_pk_bf16_f32 v46, v46, v47
	v_cvt_pk_bf16_f32 v47, v28, v29
	v_lshlrev_b32_e32 v28, 16, v38
	v_and_b32_e32 v29, 0xffff0000, v38
	v_lshlrev_b32_e32 v36, 16, v39
	v_and_b32_e32 v37, 0xffff0000, v39
	v_lshlrev_b32_e32 v38, 16, v30
	v_and_b32_e32 v39, 0xffff0000, v30
	v_lshlrev_b32_e32 v30, 16, v31
	v_and_b32_e32 v31, 0xffff0000, v31
	ds_write_b128 v120, v[44:47] offset:8704
	v_pk_mul_f32 v[28:29], v[110:111], v[28:29] op_sel_hi:[0,1]
	v_pk_mul_f32 v[36:37], v[110:111], v[36:37] op_sel_hi:[0,1]
	v_pk_mul_f32 v[38:39], v[110:111], v[38:39] op_sel_hi:[0,1]
	v_pk_mul_f32 v[44:45], v[110:111], v[30:31] op_sel_hi:[0,1]
	v_cvt_pk_bf16_f32 v28, v28, v29
	v_cvt_pk_bf16_f32 v29, v36, v37
	v_cvt_pk_bf16_f32 v30, v38, v39
	v_cvt_pk_bf16_f32 v31, v44, v45
	ds_write_b128 v120, v[28:31] offset:8720
	v_add3_u32 v28, s37, v90, v80
	v_mul_f32_e32 v29, v117, v128
	v_add3_u32 v28, v28, v81, v82
	v_cvt_pk_bf16_f32 v29, v29, s0
	v_add_u32_e32 v230, v28, v222
	v_add_u32_e32 v231, v28, v223
	v_add_u32_e32 v232, v28, v224
	v_add_u32_e32 v233, v28, v225
	v_add_u32_e32 v234, v28, v226
	v_add_u32_e32 v235, v28, v227
	v_add_u32_e32 v236, v28, v228
	v_add_u32_e32 v237, v28, v229
	ds_write_b16 v230, v29 offset:17408
	v_mul_f32_e32 v29, v117, v129
	v_cvt_pk_bf16_f32 v29, v29, s0
	ds_write_b16 v231, v29 offset:18048
	v_mul_f32_e32 v29, v117, v48
	v_cvt_pk_bf16_f32 v29, v29, s0
	ds_write_b16 v232, v29 offset:18688
	v_mul_f32_e32 v29, v117, v49
	v_cvt_pk_bf16_f32 v29, v29, s0
	ds_write_b16 v233, v29 offset:19328
	v_mul_f32_e32 v29, v117, v124
	v_cvt_pk_bf16_f32 v29, v29, s0
	ds_write_b16 v234, v29 offset:19968
	v_mul_f32_e32 v29, v117, v125
	v_cvt_pk_bf16_f32 v29, v29, s0
	ds_write_b16 v235, v29 offset:20608
	v_mul_f32_e32 v29, v117, v50
	v_cvt_pk_bf16_f32 v29, v29, s0
	ds_write_b16 v236, v29 offset:21248
	v_mul_f32_e32 v29, v117, v51
	v_cvt_pk_bf16_f32 v29, v29, s0
	ds_write_b16 v237, v29 offset:21888
	v_mul_f32_e32 v29, v117, v130
	v_cvt_pk_bf16_f32 v29, v29, s0
	ds_write_b16 v230, v29 offset:22528
	v_mul_f32_e32 v29, v117, v131
	v_cvt_pk_bf16_f32 v29, v29, s0
	ds_write_b16 v231, v29 offset:23168
	v_mul_f32_e32 v29, v117, v134
	v_cvt_pk_bf16_f32 v29, v29, s0
	ds_write_b16 v232, v29 offset:23808
	v_mul_f32_e32 v29, v117, v135
	v_cvt_pk_bf16_f32 v29, v29, s0
	ds_write_b16 v233, v29 offset:24448
	v_mul_f32_e32 v29, v117, v132
	v_cvt_pk_bf16_f32 v29, v29, s0
	ds_write_b16 v234, v29 offset:25088
	v_mul_f32_e32 v29, v117, v133
	v_cvt_pk_bf16_f32 v29, v29, s0
	ds_write_b16 v235, v29 offset:25728
	v_mul_f32_e32 v29, v117, v138
	v_cvt_pk_bf16_f32 v29, v29, s0
	ds_write_b16 v236, v29 offset:26368
	v_mul_f32_e32 v29, v117, v139
	v_cvt_pk_bf16_f32 v29, v29, s0
	ds_write_b16 v237, v29 offset:27008
	v_lshlrev_b32_e32 v28, 16, v16
	v_and_b32_e32 v29, 0xffff0000, v16
	v_lshlrev_b32_e32 v16, 16, v17
	v_and_b32_e32 v17, 0xffff0000, v17
	v_pk_mul_f32 v[30:31], v[116:117], v[16:17] op_sel_hi:[0,1]
	v_lshlrev_b32_e32 v16, 16, v18
	v_and_b32_e32 v17, 0xffff0000, v18
	v_lshlrev_b32_e32 v18, 16, v19
	v_and_b32_e32 v19, 0xffff0000, v19
	v_add3_u32 v110, s37, v88, v111
	v_pk_mul_f32 v[16:17], v[116:117], v[16:17] op_sel_hi:[0,1]
	v_pk_mul_f32 v[18:19], v[116:117], v[18:19] op_sel_hi:[0,1]
	s_and_b32 s26, s15, 32
	ds_write_b128 v110, v[16:19] offset:32784
	v_lshlrev_b32_e32 v16, 16, v12
	v_and_b32_e32 v17, 0xffff0000, v12
	v_lshlrev_b32_e32 v12, 16, v13
	v_and_b32_e32 v13, 0xffff0000, v13
	s_mulk_i32 s26, 0x210
	v_pk_mul_f32 v[16:17], v[116:117], v[16:17] op_sel_hi:[0,1]
	v_pk_mul_f32 v[18:19], v[116:117], v[12:13] op_sel_hi:[0,1]
	v_add_u32_e32 v44, s26, v89
	ds_write_b128 v110, v[16:19] offset:32800
	ds_read_b128 v[16:19], v44
	v_pk_mul_f32 v[28:29], v[116:117], v[28:29] op_sel_hi:[0,1]
	ds_write_b128 v110, v[28:31] offset:32768
	ds_read_b128 v[28:31], v44 offset:16
	ds_read_b128 v[36:39], v44 offset:32
	ds_read_b128 v[44:47], v44 offset:48
	v_lshlrev_b32_e32 v12, 16, v14
	s_waitcnt lgkmcnt(4)
; #define LAS __attribute__((address_space(3)))
; __device__ __forceinline__ float rsq_f(float x) { return __builtin_amdgcn_rsqf(x); }
; __device__ __forceinline__ float red8(float x) { x += dpp_f<0xB1>(x); x += dpp_f<0x4E>(x); x += dpp_f<0x141>(x); return x; }
; __device__ __forceinline__ void unpack8(const u32x4 u, float* x) { x[0] = bflo(u.x); x[1] = bfhi(u.x); x[2] = bflo(u.y); x[3] = bfhi(u.y); x[4] = bflo(u.z); x[5] = bfhi(u.z); x[6] = bflo(u.w); x[7] = bfhi(u.w); }
; __device__ __forceinline__ void delta_out_norm(const LAS float* ob, int pt, const float* dn16, const u32x4 z0, const u32x4 z1, bf16* dst) {
;     const LAS float* p = ob + (pt >> 3) * 132 + (pt & 7) * 16;
;     float o[16], z[16];
; #pragma unroll
;     for (int e4 = 0; e4 < 4; ++e4) { const f32x4 t = *(const LAS f32x4*)(p + 4 * e4); o[4 * e4] = t[0]; o[4 * e4 + 1] = t[1]; o[4 * e4 + 2] = t[2]; o[4 * e4 + 3] = t[3]; }
;     float ss = 0.f;
; #pragma unroll
;     for (int e = 0; e < 16; ++e) ss += o[e] * o[e];
;     ss = red8(ss);
;     const float rstd = rsq_f(ss * (1.f / 128.f) + EPS);
;     unpack8(z0, z); unpack8(z1, z + 8);
; #pragma unroll
;     for (int e = 0; e < 16; ++e) o[e] = o[e] * rstd * dn16[e] * z[e];
;     *(bf16x8*)dst = pack8(o[0], o[1], o[2], o[3], o[4], o[5], o[6], o[7]); *(bf16x8*)(dst + 8) = pack8(o[8], o[9], o[10], o[11], o[12], o[13], o[14], o[15]);
; }
	v_mul_f32_e32 v50, v17, v17
	v_fmac_f32_e32 v50, v16, v16
	v_fmac_f32_e32 v50, v18, v18
	v_fmac_f32_e32 v50, v19, v19
	s_waitcnt lgkmcnt(2)
	v_fmac_f32_e32 v50, v28, v28
	v_fmac_f32_e32 v50, v29, v29
	v_fmac_f32_e32 v50, v30, v30
	v_fmac_f32_e32 v50, v31, v31
	s_waitcnt lgkmcnt(1)
	v_fmac_f32_e32 v50, v36, v36
	v_fmac_f32_e32 v50, v37, v37
	v_pk_mul_f32 v[48:49], v[38:39], v[38:39]
	v_and_b32_e32 v13, 0xffff0000, v14
	v_lshlrev_b32_e32 v14, 16, v15
	v_and_b32_e32 v15, 0xffff0000, v15
	v_add_f32_e32 v48, v48, v50
	v_pk_mul_f32 v[12:13], v[116:117], v[12:13] op_sel_hi:[0,1]
	v_pk_mul_f32 v[14:15], v[116:117], v[14:15] op_sel_hi:[0,1]
	v_add_f32_e32 v116, v49, v48
	s_waitcnt lgkmcnt(0)
	v_pk_mul_f32 v[50:51], v[44:45], v[44:45]
	v_pk_mul_f32 v[48:49], v[46:47], v[46:47]
	v_add_f32_e32 v50, v50, v116
	v_add_f32_e32 v50, v51, v50
	v_add_f32_e32 v48, v48, v50
	v_add_f32_e32 v48, v49, v48
	ds_write_b128 v110, v[12:15] offset:32816
	s_waitcnt vmcnt(15)
	v_lshlrev_b32_e32 v12, 16, v8
	v_add_f32_dpp v48, v48, v48 quad_perm:[1,0,3,2] row_mask:0xf bank_mask:0xf bound_ctrl:1
	v_and_b32_e32 v13, 0xffff0000, v8
	v_lshlrev_b32_e32 v8, 16, v9
	v_add_f32_dpp v48, v48, v48 quad_perm:[2,3,0,1] row_mask:0xf bank_mask:0xf bound_ctrl:1
	v_and_b32_e32 v9, 0xffff0000, v9
	s_add_i32 s36, s36, 1
	v_add_f32_dpp v48, v48, v48 row_half_mirror row_mask:0xf bank_mask:0xf bound_ctrl:1
	v_fmamk_f32 v48, v48, 0x3c000000, v83
	v_rsq_f32_e32 v48, v48
	s_add_u32 s12, s12, 0x10000
	s_addc_u32 s13, s13, 0
	s_add_u32 s4, s4, 0x80
	v_pk_mul_f32 v[14:15], v[16:17], v[48:49] op_sel_hi:[1,0]
	v_pk_mul_f32 v[16:17], v[28:29], v[48:49] op_sel_hi:[1,0]
	v_pk_mul_f32 v[14:15], v[102:103], v[14:15]
	v_pk_mul_f32 v[16:17], v[98:99], v[16:17]
	v_pk_mul_f32 v[12:13], v[14:15], v[12:13]
	v_pk_mul_f32 v[14:15], v[18:19], v[48:49] op_sel_hi:[1,0]
	v_pk_mul_f32 v[18:19], v[36:37], v[48:49] op_sel_hi:[1,0]
	v_pk_mul_f32 v[14:15], v[100:101], v[14:15]
	v_pk_mul_f32 v[18:19], v[94:95], v[18:19]
	v_pk_mul_f32 v[8:9], v[14:15], v[8:9]
	v_lshlrev_b32_e32 v14, 16, v10
	v_and_b32_e32 v15, 0xffff0000, v10
	v_pk_mul_f32 v[14:15], v[16:17], v[14:15]
	v_pk_mul_f32 v[16:17], v[30:31], v[48:49] op_sel_hi:[1,0]
	v_lshlrev_b32_e32 v10, 16, v11
	v_and_b32_e32 v11, 0xffff0000, v11
	v_pk_mul_f32 v[16:17], v[96:97], v[16:17]
	v_pk_mul_f32 v[28:29], v[44:45], v[48:49] op_sel_hi:[1,0]
	v_pk_mul_f32 v[10:11], v[16:17], v[10:11]
	s_waitcnt vmcnt(14)
	v_lshlrev_b32_e32 v16, 16, v4
	v_and_b32_e32 v17, 0xffff0000, v4
	v_pk_mul_f32 v[16:17], v[18:19], v[16:17]
	v_pk_mul_f32 v[18:19], v[38:39], v[48:49] op_sel_hi:[1,0]
	v_lshlrev_b32_e32 v4, 16, v5
	v_and_b32_e32 v5, 0xffff0000, v5
	v_pk_mul_f32 v[18:19], v[92:93], v[18:19]
	v_pk_mul_f32 v[28:29], v[104:105], v[28:29]
	v_pk_mul_f32 v[18:19], v[18:19], v[4:5]
	v_lshlrev_b32_e32 v4, 16, v6
	v_and_b32_e32 v5, 0xffff0000, v6
	v_pk_mul_f32 v[28:29], v[28:29], v[4:5]
	v_lshlrev_b32_e32 v4, 16, v7
	v_and_b32_e32 v5, 0xffff0000, v7
	v_pk_mul_f32 v[6:7], v[46:47], v[48:49] op_sel_hi:[1,0]
	s_addc_u32 s5, s5, 0
	v_pk_mul_f32 v[6:7], v[106:107], v[6:7]
	s_add_i32 s15, s15, 32
	v_pk_mul_f32 v[30:31], v[6:7], v[4:5]
	v_cvt_pk_bf16_f32 v5, v8, v9
	v_add_co_u32_e32 v8, vcc, s31, v78
	v_cvt_pk_bf16_f32 v4, v12, v13
	v_cvt_pk_bf16_f32 v6, v14, v15
	v_cvt_pk_bf16_f32 v7, v10, v11
	v_addc_co_u32_e32 v9, vcc, 0, v79, vcc
	global_store_dwordx4 v[8:9], v[4:7], off
	s_cmp_eq_u32 s12, 0x3d0000
	v_lshl_add_u64 v[70:71], v[70:71], 0, s[24:25]
	v_cvt_pk_bf16_f32 v4, v16, v17
	v_cvt_pk_bf16_f32 v5, v18, v19
	v_cvt_pk_bf16_f32 v6, v28, v29
	v_cvt_pk_bf16_f32 v7, v30, v31
	global_store_dwordx4 v[8:9], v[4:7], off offset:16
	s_waitcnt lgkmcnt(0)
	s_barrier
	s_cbranch_scc1 .LBB0_1842
	s_waitcnt vmcnt(3)
	v_mov_b64_e32 v[8:9], v[24:25]
	s_waitcnt vmcnt(2)
	v_mov_b64_e32 v[4:5], v[20:21]
	v_mov_b64_e32 v[48:49], v[64:65]
	v_mov_b64_e32 v[44:45], v[60:61]
	v_mov_b64_e32 v[36:37], v[56:57]
	v_mov_b64_e32 v[28:29], v[52:53]
	v_mov_b64_e32 v[16:17], v[40:41]
	v_mov_b64_e32 v[12:13], v[32:33]
	v_mov_b64_e32 v[10:11], v[26:27]
	v_mov_b64_e32 v[6:7], v[22:23]
	v_mov_b64_e32 v[50:51], v[66:67]
	v_mov_b64_e32 v[46:47], v[62:63]
	v_mov_b64_e32 v[38:39], v[58:59]
	v_mov_b64_e32 v[30:31], v[54:55]
	v_mov_b64_e32 v[18:19], v[42:43]
	v_mov_b64_e32 v[14:15], v[34:35]
	v_mov_b32_e32 v123, v84
	v_mov_b32_e32 v124, v85
	v_mov_b32_e32 v116, v68
	v_mov_b32_e32 v125, v86
	v_mov_b32_e32 v126, v87
	s_branch .LBB0_1838

; #define LAS __attribute__((address_space(3)))
; __device__ __forceinline__ unsigned f2bf(float f) { return pk2(f, f) & 0xffffu; }
; __device__ __forceinline__ int perm16(int e) { return (e & ~12) | ((e >> 1) & 4) | ((e << 1) & 8); }
; __device__ __forceinline__ void delta_rec_stage(LAS unsigned char* buf, int pt, const DeltaPre& dp) {
;     const int tt = pt >> 3, dg = pt & 7, d0 = dg * 16;
;     { LAS bf16* dst = (LAS bf16*)(buf + (pt < 128 ? DR_TI : DR_AT)) + ((pt & 127) >> 2) * 40 + (pt & 3) * 8; *(LAS u32x4*)dst = dp.tia; }
;     if (pt == 0) *(LAS float*)(buf + DR_EGL) = __expf(dp.gl);
;     const float eg = __expf(dp.gct), ekd = __expf(dp.gl - dp.gct);
;     const float fq = dp.nq * eg, fkb = dp.nk * dp.bet * eg, fkd = dp.nk * ekd, bet = dp.bet;
;     float k[16], q[16], v[16];
;     unpack8(dp.k0, k); unpack8(dp.k1, k + 8); unpack8(dp.q0, q); unpack8(dp.q1, q + 8); unpack8(dp.v0, v); unpack8(dp.v1, v + 8);
;     LAS bf16* KB = (LAS bf16*)(buf + DR_KB) + tt * 136 + d0; LAS bf16* QD = (LAS bf16*)(buf + DR_QD) + tt * 136 + d0;
;     *(LAS bf16x8*)KB = pack8(k[0] * fkb, k[1] * fkb, k[2] * fkb, k[3] * fkb, k[8] * fkb, k[9] * fkb, k[10] * fkb, k[11] * fkb);
;     *(LAS bf16x8*)(KB + 8) = pack8(k[4] * fkb, k[5] * fkb, k[6] * fkb, k[7] * fkb, k[12] * fkb, k[13] * fkb, k[14] * fkb, k[15] * fkb);
;     *(LAS bf16x8*)QD = pack8(q[0] * fq, q[1] * fq, q[2] * fq, q[3] * fq, q[8] * fq, q[9] * fq, q[10] * fq, q[11] * fq);
;     *(LAS bf16x8*)(QD + 8) = pack8(q[4] * fq, q[5] * fq, q[6] * fq, q[7] * fq, q[12] * fq, q[13] * fq, q[14] * fq, q[15] * fq);
;     LAS bf16* KDT = (LAS bf16*)(buf + DR_KDT) + d0 * 40 + perm16(tt);
; #pragma unroll
;     for (int e = 0; e < 16; ++e) KDT[e * 40] = (bf16)f2bf(k[e] * fkd);
;     LAS float* VB = (LAS float*)(buf + DR_VB) + tt * 132 + d0;
; #pragma unroll
;     for (int e4 = 0; e4 < 4; ++e4) *(LAS f32x4*)(VB + 4 * e4) = (f32x4){v[4 * e4] * bet, v[4 * e4 + 1] * bet, v[4 * e4 + 2] * bet, v[4 * e4 + 3] * bet};
; }
; __device__ __forceinline__ void delta_out_norm(const LAS float* ob, int pt, const float* dn16, const u32x4 z0, const u32x4 z1, bf16* dst) {
;     const LAS float* p = ob + (pt >> 3) * 132 + (pt & 7) * 16;
;     float o[16], z[16];
; #pragma unroll
;     for (int e4 = 0; e4 < 4; ++e4) { const f32x4 t = *(const LAS f32x4*)(p + 4 * e4); o[4 * e4] = t[0]; o[4 * e4 + 1] = t[1]; o[4 * e4 + 2] = t[2]; o[4 * e4 + 3] = t[3]; }
.LBB0_1844:
	s_or_b64 exec, exec, s[4:5]
	v_mul_f32_e32 v0, 0x3fb8aa3b, v84
	v_sub_f32_e32 v1, v85, v84
	v_exp_f32_e32 v0, v0
	v_mul_f32_e32 v1, 0x3fb8aa3b, v1
	v_exp_f32_e32 v1, v1
	v_mul_f32_e32 v2, v68, v86
	v_mul_f32_e32 v16, v0, v2
	v_lshlrev_b32_e32 v18, 16, v64
	v_and_b32_e32 v19, 0xffff0000, v64
	v_lshlrev_b32_e32 v28, 16, v65
	v_and_b32_e32 v29, 0xffff0000, v65
	v_lshlrev_b32_e32 v30, 16, v60
	v_and_b32_e32 v31, 0xffff0000, v60
	v_lshlrev_b32_e32 v38, 16, v61
	v_and_b32_e32 v39, 0xffff0000, v61
	v_mul_f32_e32 v14, v0, v87
	v_mul_f32_e32 v69, v86, v1
	v_pk_mul_f32 v[0:1], v[16:17], v[18:19] op_sel_hi:[0,1]
	v_pk_mul_f32 v[2:3], v[16:17], v[28:29] op_sel_hi:[0,1]
	v_pk_mul_f32 v[36:37], v[16:17], v[30:31] op_sel_hi:[0,1]
	v_pk_mul_f32 v[44:45], v[16:17], v[38:39] op_sel_hi:[0,1]
	v_add3_u32 v70, s12, v91, v114
	v_cvt_pk_bf16_f32 v0, v0, v1
	v_cvt_pk_bf16_f32 v1, v2, v3
	v_cvt_pk_bf16_f32 v2, v36, v37
	v_cvt_pk_bf16_f32 v3, v44, v45
	v_lshlrev_b32_e32 v36, 16, v66
	v_and_b32_e32 v37, 0xffff0000, v66
	v_lshlrev_b32_e32 v44, 16, v67
	v_and_b32_e32 v45, 0xffff0000, v67
	v_lshlrev_b32_e32 v46, 16, v62
	v_and_b32_e32 v47, 0xffff0000, v62
	v_lshlrev_b32_e32 v50, 16, v63
	v_and_b32_e32 v51, 0xffff0000, v63
	ds_write_b128 v70, v[0:3]
	v_pk_mul_f32 v[0:1], v[16:17], v[36:37] op_sel_hi:[0,1]
	v_pk_mul_f32 v[2:3], v[16:17], v[44:45] op_sel_hi:[0,1]
	v_pk_mul_f32 v[48:49], v[16:17], v[46:47] op_sel_hi:[0,1]
	v_pk_mul_f32 v[16:17], v[16:17], v[50:51] op_sel_hi:[0,1]
	v_cvt_pk_bf16_f32 v0, v0, v1
	v_cvt_pk_bf16_f32 v1, v2, v3
	v_cvt_pk_bf16_f32 v2, v48, v49
	v_cvt_pk_bf16_f32 v3, v16, v17
	ds_write_b128 v70, v[0:3] offset:16
	v_lshlrev_b32_e32 v0, 16, v56
	v_and_b32_e32 v1, 0xffff0000, v56
	v_lshlrev_b32_e32 v2, 16, v57
	v_and_b32_e32 v3, 0xffff0000, v57
	v_lshlrev_b32_e32 v16, 16, v52
	v_and_b32_e32 v17, 0xffff0000, v52
	v_lshlrev_b32_e32 v48, 16, v53
	v_and_b32_e32 v49, 0xffff0000, v53
	v_pk_mul_f32 v[0:1], v[14:15], v[0:1] op_sel_hi:[0,1]
	v_pk_mul_f32 v[2:3], v[14:15], v[2:3] op_sel_hi:[0,1]
	v_pk_mul_f32 v[16:17], v[14:15], v[16:17] op_sel_hi:[0,1]
	v_pk_mul_f32 v[48:49], v[14:15], v[48:49] op_sel_hi:[0,1]
	v_cvt_pk_bf16_f32 v0, v0, v1
	v_cvt_pk_bf16_f32 v1, v2, v3
	v_cvt_pk_bf16_f32 v2, v16, v17
	v_cvt_pk_bf16_f32 v3, v48, v49
	ds_write_b128 v70, v[0:3] offset:8704
	v_lshlrev_b32_e32 v0, 16, v58
	v_and_b32_e32 v1, 0xffff0000, v58
	v_lshlrev_b32_e32 v2, 16, v59
	v_and_b32_e32 v3, 0xffff0000, v59
	v_lshlrev_b32_e32 v16, 16, v54
	v_and_b32_e32 v17, 0xffff0000, v54
	v_lshlrev_b32_e32 v48, 16, v55
	v_and_b32_e32 v49, 0xffff0000, v55
	v_pk_mul_f32 v[0:1], v[14:15], v[0:1] op_sel_hi:[0,1]
	v_pk_mul_f32 v[2:3], v[14:15], v[2:3] op_sel_hi:[0,1]
	v_pk_mul_f32 v[16:17], v[14:15], v[16:17] op_sel_hi:[0,1]
	v_pk_mul_f32 v[14:15], v[14:15], v[48:49] op_sel_hi:[0,1]
	v_cvt_pk_bf16_f32 v0, v0, v1
	v_cvt_pk_bf16_f32 v1, v2, v3
	v_cvt_pk_bf16_f32 v2, v16, v17
	v_cvt_pk_bf16_f32 v3, v14, v15
	ds_write_b128 v70, v[0:3] offset:8720
	v_add3_u32 v0, s12, v90, v80
	v_mul_f32_e32 v1, v69, v18
	v_add3_u32 v0, v0, v81, v82
	v_cvt_pk_bf16_f32 v1, v1, s0
	v_add_u32_e32 v230, v0, v222
	v_add_u32_e32 v231, v0, v223
	v_add_u32_e32 v232, v0, v224
	v_add_u32_e32 v233, v0, v225
	v_add_u32_e32 v234, v0, v226
	v_add_u32_e32 v235, v0, v227
	v_add_u32_e32 v236, v0, v228
	v_add_u32_e32 v237, v0, v229
	ds_write_b16 v230, v1 offset:17408
	v_mul_f32_e32 v1, v69, v19
	v_cvt_pk_bf16_f32 v1, v1, s0
	ds_write_b16 v231, v1 offset:18048
	v_mul_f32_e32 v1, v69, v28
	v_cvt_pk_bf16_f32 v1, v1, s0
	ds_write_b16 v232, v1 offset:18688
	v_mul_f32_e32 v1, v69, v29
	v_cvt_pk_bf16_f32 v1, v1, s0
	ds_write_b16 v233, v1 offset:19328
	v_mul_f32_e32 v1, v69, v36
	v_cvt_pk_bf16_f32 v1, v1, s0
	ds_write_b16 v234, v1 offset:19968
	v_mul_f32_e32 v1, v69, v37
	v_cvt_pk_bf16_f32 v1, v1, s0
	ds_write_b16 v235, v1 offset:20608
	v_mul_f32_e32 v1, v69, v44
	v_cvt_pk_bf16_f32 v1, v1, s0
	ds_write_b16 v236, v1 offset:21248
	v_mul_f32_e32 v1, v69, v45
	v_cvt_pk_bf16_f32 v1, v1, s0
	ds_write_b16 v237, v1 offset:21888
	v_mul_f32_e32 v1, v69, v30
	v_cvt_pk_bf16_f32 v1, v1, s0
	ds_write_b16 v230, v1 offset:22528
	v_mul_f32_e32 v1, v69, v31
	v_cvt_pk_bf16_f32 v1, v1, s0
	ds_write_b16 v231, v1 offset:23168
	v_mul_f32_e32 v1, v69, v38
	v_cvt_pk_bf16_f32 v1, v1, s0
	ds_write_b16 v232, v1 offset:23808
	v_mul_f32_e32 v1, v69, v39
	v_cvt_pk_bf16_f32 v1, v1, s0
	ds_write_b16 v233, v1 offset:24448
	v_mul_f32_e32 v1, v69, v46
	v_cvt_pk_bf16_f32 v1, v1, s0
	ds_write_b16 v234, v1 offset:25088
	v_mul_f32_e32 v1, v69, v47
	v_cvt_pk_bf16_f32 v1, v1, s0
	ds_write_b16 v235, v1 offset:25728
	v_mul_f32_e32 v1, v69, v50
	v_cvt_pk_bf16_f32 v1, v1, s0
	ds_write_b16 v236, v1 offset:26368
	v_mul_f32_e32 v1, v69, v51
	v_cvt_pk_bf16_f32 v1, v1, s0
	ds_write_b16 v237, v1 offset:27008
	v_lshlrev_b32_e32 v0, 16, v40
	v_and_b32_e32 v1, 0xffff0000, v40
	v_lshlrev_b32_e32 v2, 16, v41
	v_and_b32_e32 v3, 0xffff0000, v41
	v_add3_u32 v14, s12, v88, v111
	v_pk_mul_f32 v[0:1], v[68:69], v[0:1] op_sel_hi:[0,1]
	v_pk_mul_f32 v[2:3], v[68:69], v[2:3] op_sel_hi:[0,1]
	ds_write_b128 v14, v[0:3] offset:32768
	v_lshlrev_b32_e32 v0, 16, v42
	v_and_b32_e32 v1, 0xffff0000, v42
	v_lshlrev_b32_e32 v2, 16, v43
	v_and_b32_e32 v3, 0xffff0000, v43
	v_pk_mul_f32 v[0:1], v[68:69], v[0:1] op_sel_hi:[0,1]
	v_pk_mul_f32 v[2:3], v[68:69], v[2:3] op_sel_hi:[0,1]
	ds_write_b128 v14, v[0:3] offset:32784
	v_lshlrev_b32_e32 v0, 16, v32
	v_and_b32_e32 v1, 0xffff0000, v32
	v_lshlrev_b32_e32 v2, 16, v33
	v_and_b32_e32 v3, 0xffff0000, v33
	v_pk_mul_f32 v[0:1], v[68:69], v[0:1] op_sel_hi:[0,1]
	v_pk_mul_f32 v[2:3], v[68:69], v[2:3] op_sel_hi:[0,1]
	ds_write_b128 v14, v[0:3] offset:32800
	v_lshlrev_b32_e32 v0, 16, v34
	v_and_b32_e32 v1, 0xffff0000, v34
	v_lshlrev_b32_e32 v2, 16, v35
	v_and_b32_e32 v3, 0xffff0000, v35
	v_pk_mul_f32 v[0:1], v[68:69], v[0:1] op_sel_hi:[0,1]
	v_pk_mul_f32 v[2:3], v[68:69], v[2:3] op_sel_hi:[0,1]
	ds_write_b128 v14, v[0:3] offset:32816
	ds_read_b128 v[0:3], v89 offset:16896
	ds_read_b128 v[14:17], v89 offset:16912
	ds_read_b128 v[28:31], v89 offset:16928
	ds_read_b128 v[32:35], v89 offset:16944
	v_mov_b32_e32 v40, 0x358637bd
	s_waitcnt vmcnt(5)
; #define LAS __attribute__((address_space(3)))
; __device__ __forceinline__ float rsq_f(float x) { return __builtin_amdgcn_rsqf(x); }
; __device__ __forceinline__ float red8(float x) { x += dpp_f<0xB1>(x); x += dpp_f<0x4E>(x); x += dpp_f<0x141>(x); return x; }
; __device__ __forceinline__ void unpack8(const u32x4 u, float* x) { x[0] = bflo(u.x); x[1] = bfhi(u.x); x[2] = bflo(u.y); x[3] = bfhi(u.y); x[4] = bflo(u.z); x[5] = bfhi(u.z); x[6] = bflo(u.w); x[7] = bfhi(u.w); }
; #define DR_BAR() do { asm volatile("s_waitcnt lgkmcnt(0)" ::: "memory"); __builtin_amdgcn_s_barrier(); asm volatile("" ::: "memory"); } while (0)
; __device__ __forceinline__ void delta_out_norm(const LAS float* ob, int pt, const float* dn16, const u32x4 z0, const u32x4 z1, bf16* dst) {
;     const LAS float* p = ob + (pt >> 3) * 132 + (pt & 7) * 16;
;     float o[16], z[16];
; #pragma unroll
;     for (int e4 = 0; e4 < 4; ++e4) { const f32x4 t = *(const LAS f32x4*)(p + 4 * e4); o[4 * e4] = t[0]; o[4 * e4 + 1] = t[1]; o[4 * e4 + 2] = t[2]; o[4 * e4 + 3] = t[3]; }
;     float ss = 0.f;
; #pragma unroll
;     for (int e = 0; e < 16; ++e) ss += o[e] * o[e];
;     ss = red8(ss);
;     const float rstd = rsq_f(ss * (1.f / 128.f) + EPS);
;     unpack8(z0, z); unpack8(z1, z + 8);
; #pragma unroll
;     for (int e = 0; e < 16; ++e) o[e] = o[e] * rstd * dn16[e] * z[e];
;     *(bf16x8*)dst = pack8(o[0], o[1], o[2], o[3], o[4], o[5], o[6], o[7]); *(bf16x8*)(dst + 8) = pack8(o[8], o[9], o[10], o[11], o[12], o[13], o[14], o[15]);
; }
; __device__ __forceinline__ void delta_rec_task(const Params& P, LAS unsigned char* lds, int b, int h, int tid) {
;     ...
;         for (int c = 0; c < NC; ++c) {
;             if (c > 0) { dcur = dnxt; zc0 = zn0; zc1 = zn1; }
;             if (c + 2 < NC) delta_pre_load(b, h, c + 2, pt, dnxt);
;             zn0 = *(const u32x4*)(zgp + (size_t)c * 32 * D); zn1 = *(const u32x4*)(zgp + (size_t)c * 32 * D + 8);
;             if (c + 1 < NC) delta_rec_stage(lds + ((c + 1) & 1) * DR_BUF, pt, dcur);
;             if (c > 0) delta_out_norm((const LAS float*)(lds + DR_OB) + ((c - 1) & 1) * 32 * 132, pt, dn16, zc0, zc1, zgp + (size_t)(c - 1) * 32 * D);
;             DR_BAR();
;         }
;         delta_out_norm((const LAS float*)(lds + DR_OB) + ((NC - 1) & 1) * 32 * 132, pt, dn16, zn0, zn1, zgp + (size_t)(NC - 1) * 32 * D);
	v_and_b32_e32 v39, 0xffff0000, v24
	s_mov_b64 s[4:5], 0x3d0000
	s_waitcnt lgkmcnt(3)
	v_mul_f32_e32 v36, v1, v1
	v_fmac_f32_e32 v36, v0, v0
	v_fmac_f32_e32 v36, v2, v2
	v_fmac_f32_e32 v36, v3, v3
	s_waitcnt lgkmcnt(2)
	v_fmac_f32_e32 v36, v14, v14
	v_fmac_f32_e32 v36, v15, v15
	v_fmac_f32_e32 v36, v16, v16
	v_fmac_f32_e32 v36, v17, v17
	s_waitcnt lgkmcnt(1)
	v_fmac_f32_e32 v36, v28, v28
	v_fmac_f32_e32 v36, v29, v29
	v_pk_mul_f32 v[18:19], v[30:31], v[30:31]
	s_nop 0
	v_add_f32_e32 v18, v18, v36
	v_add_f32_e32 v38, v19, v18
	s_waitcnt lgkmcnt(0)
	v_pk_mul_f32 v[36:37], v[32:33], v[32:33]
	v_pk_mul_f32 v[18:19], v[34:35], v[34:35]
	v_add_f32_e32 v36, v36, v38
	v_add_f32_e32 v36, v37, v36
	v_add_f32_e32 v18, v18, v36
	v_add_f32_e32 v18, v19, v18
	v_lshlrev_b32_e32 v38, 16, v24
	v_lshlrev_b32_e32 v24, 16, v25
	v_add_f32_dpp v18, v18, v18 quad_perm:[1,0,3,2] row_mask:0xf bank_mask:0xf bound_ctrl:1
	v_and_b32_e32 v25, 0xffff0000, v25
	v_lshl_add_u64 v[36:37], v[108:109], 0, s[4:5]
	v_add_f32_dpp v18, v18, v18 quad_perm:[2,3,0,1] row_mask:0xf bank_mask:0xf bound_ctrl:1
	s_mov_b32 s4, 0x3d0000
	s_nop 0
	v_add_f32_dpp v18, v18, v18 row_half_mirror row_mask:0xf bank_mask:0xf bound_ctrl:1
	v_fmamk_f32 v18, v18, 0x3c000000, v40
	v_rsq_f32_e32 v18, v18
	s_nop 0
	v_pk_mul_f32 v[2:3], v[2:3], v[18:19] op_sel_hi:[1,0]
	s_nop 0
	v_pk_mul_f32 v[2:3], v[100:101], v[2:3]
	v_pk_mul_f32 v[14:15], v[14:15], v[18:19] op_sel_hi:[1,0]
	v_pk_mul_f32 v[2:3], v[2:3], v[24:25]
	v_lshlrev_b32_e32 v24, 16, v26
	v_and_b32_e32 v25, 0xffff0000, v26
	v_pk_mul_f32 v[14:15], v[98:99], v[14:15]
	v_pk_mul_f32 v[16:17], v[16:17], v[18:19] op_sel_hi:[1,0]
	v_pk_mul_f32 v[14:15], v[14:15], v[24:25]
	v_lshlrev_b32_e32 v24, 16, v27
	v_and_b32_e32 v25, 0xffff0000, v27
	v_pk_mul_f32 v[16:17], v[96:97], v[16:17]
	v_pk_mul_f32 v[26:27], v[28:29], v[18:19] op_sel_hi:[1,0]
	v_pk_mul_f32 v[0:1], v[0:1], v[18:19] op_sel_hi:[1,0]
	v_pk_mul_f32 v[16:17], v[16:17], v[24:25]
	s_waitcnt vmcnt(4)
	v_lshlrev_b32_e32 v24, 16, v20
	v_and_b32_e32 v25, 0xffff0000, v20
	v_pk_mul_f32 v[26:27], v[94:95], v[26:27]
	v_pk_mul_f32 v[0:1], v[102:103], v[0:1]
	v_pk_mul_f32 v[24:25], v[26:27], v[24:25]
	v_pk_mul_f32 v[26:27], v[30:31], v[18:19] op_sel_hi:[1,0]
	v_pk_mul_f32 v[0:1], v[0:1], v[38:39]
	v_lshlrev_b32_e32 v20, 16, v21
	v_and_b32_e32 v21, 0xffff0000, v21
	v_pk_mul_f32 v[26:27], v[92:93], v[26:27]
	v_pk_mul_f32 v[28:29], v[32:33], v[18:19] op_sel_hi:[1,0]
	v_pk_mul_f32 v[18:19], v[34:35], v[18:19] op_sel_hi:[1,0]
	v_pk_mul_f32 v[20:21], v[26:27], v[20:21]
	v_lshlrev_b32_e32 v26, 16, v22
	v_and_b32_e32 v27, 0xffff0000, v22
	v_pk_mul_f32 v[28:29], v[104:105], v[28:29]
	v_lshlrev_b32_e32 v22, 16, v23
	v_and_b32_e32 v23, 0xffff0000, v23
	v_pk_mul_f32 v[18:19], v[106:107], v[18:19]
	v_cvt_pk_bf16_f32 v0, v0, v1
	v_cvt_pk_bf16_f32 v1, v2, v3
	v_cvt_pk_bf16_f32 v2, v14, v15
	v_add_co_u32_e32 v14, vcc, s4, v108
	v_pk_mul_f32 v[26:27], v[28:29], v[26:27]
	v_pk_mul_f32 v[18:19], v[18:19], v[22:23]
	v_cvt_pk_bf16_f32 v3, v16, v17
	v_addc_co_u32_e32 v15, vcc, 0, v109, vcc
	global_store_dwordx4 v[14:15], v[0:3], off
	s_mov_b64 s[4:5], 0x3f0000
	v_lshl_add_u64 v[34:35], v[108:109], 0, s[4:5]
	v_cvt_pk_bf16_f32 v0, v24, v25
	v_cvt_pk_bf16_f32 v1, v20, v21
	v_cvt_pk_bf16_f32 v2, v26, v27
	v_cvt_pk_bf16_f32 v3, v18, v19
	global_store_dwordx4 v[36:37], v[0:3], off offset:16
	s_waitcnt lgkmcnt(0)
	s_barrier
	ds_read_b128 v[0:3], v89
	ds_read_b128 v[14:17], v89 offset:16
	ds_read_b128 v[18:21], v89 offset:32
	ds_read_b128 v[22:25], v89 offset:48
	s_mov_b32 s4, 0x3f0000
	v_add_co_u32_e32 v36, vcc, s4, v108
	s_waitcnt lgkmcnt(3)
	v_mul_f32_e32 v28, v1, v1
	v_fmac_f32_e32 v28, v0, v0
	v_fmac_f32_e32 v28, v2, v2
	v_fmac_f32_e32 v28, v3, v3
	s_waitcnt lgkmcnt(2)
	v_fmac_f32_e32 v28, v14, v14
	v_fmac_f32_e32 v28, v15, v15
	v_fmac_f32_e32 v28, v16, v16
	v_fmac_f32_e32 v28, v17, v17
	s_waitcnt lgkmcnt(1)
	v_fmac_f32_e32 v28, v18, v18
	v_fmac_f32_e32 v28, v19, v19
	v_pk_mul_f32 v[26:27], v[20:21], v[20:21]
	v_addc_co_u32_e32 v37, vcc, 0, v109, vcc
	v_add_f32_e32 v26, v26, v28
	v_add_f32_e32 v30, v27, v26
	s_waitcnt lgkmcnt(0)
	v_pk_mul_f32 v[28:29], v[22:23], v[22:23]
	v_pk_mul_f32 v[26:27], v[24:25], v[24:25]
	v_add_f32_e32 v28, v28, v30
	v_add_f32_e32 v28, v29, v28
	v_add_f32_e32 v26, v26, v28
	v_add_f32_e32 v26, v27, v26
	s_nop 1
	v_add_f32_dpp v26, v26, v26 quad_perm:[1,0,3,2] row_mask:0xf bank_mask:0xf bound_ctrl:1
	s_nop 1
	v_add_f32_dpp v26, v26, v26 quad_perm:[2,3,0,1] row_mask:0xf bank_mask:0xf bound_ctrl:1
	s_nop 1
	v_add_f32_dpp v26, v26, v26 row_half_mirror row_mask:0xf bank_mask:0xf bound_ctrl:1
	v_fmamk_f32 v26, v26, 0x3c000000, v40
	v_rsq_f32_e32 v38, v26
	global_load_dwordx4 v[26:29], v[36:37], off
	global_load_dwordx4 v[30:33], v[34:35], off offset:16
	s_waitcnt vmcnt(5)
	v_lshlrev_b32_e32 v34, 16, v8
	v_and_b32_e32 v35, 0xffff0000, v8
	v_pk_mul_f32 v[2:3], v[2:3], v[38:39] op_sel_hi:[1,0]
	v_lshlrev_b32_e32 v8, 16, v9
	v_and_b32_e32 v9, 0xffff0000, v9
	v_pk_mul_f32 v[2:3], v[100:101], v[2:3]
	v_pk_mul_f32 v[14:15], v[14:15], v[38:39] op_sel_hi:[1,0]
	v_pk_mul_f32 v[2:3], v[2:3], v[8:9]
	v_lshlrev_b32_e32 v8, 16, v10
	v_and_b32_e32 v9, 0xffff0000, v10
	v_pk_mul_f32 v[14:15], v[98:99], v[14:15]
	v_lshlrev_b32_e32 v10, 16, v11
	v_pk_mul_f32 v[8:9], v[14:15], v[8:9]
	v_pk_mul_f32 v[14:15], v[16:17], v[38:39] op_sel_hi:[1,0]
	v_and_b32_e32 v11, 0xffff0000, v11
	v_pk_mul_f32 v[14:15], v[96:97], v[14:15]
	v_pk_mul_f32 v[16:17], v[18:19], v[38:39] op_sel_hi:[1,0]
	v_pk_mul_f32 v[10:11], v[14:15], v[10:11]
	s_waitcnt vmcnt(4)
	v_lshlrev_b32_e32 v14, 16, v4
	v_and_b32_e32 v15, 0xffff0000, v4
	v_pk_mul_f32 v[16:17], v[94:95], v[16:17]
	v_pk_mul_f32 v[0:1], v[0:1], v[38:39] op_sel_hi:[1,0]
	v_pk_mul_f32 v[14:15], v[16:17], v[14:15]
	v_pk_mul_f32 v[16:17], v[20:21], v[38:39] op_sel_hi:[1,0]
	v_lshlrev_b32_e32 v4, 16, v5
	v_and_b32_e32 v5, 0xffff0000, v5
	v_pk_mul_f32 v[16:17], v[92:93], v[16:17]
	v_pk_mul_f32 v[18:19], v[22:23], v[38:39] op_sel_hi:[1,0]
	v_pk_mul_f32 v[0:1], v[102:103], v[0:1]
	v_pk_mul_f32 v[4:5], v[16:17], v[4:5]
	v_lshlrev_b32_e32 v16, 16, v6
	v_and_b32_e32 v17, 0xffff0000, v6
	v_pk_mul_f32 v[18:19], v[104:105], v[18:19]
	v_pk_mul_f32 v[0:1], v[0:1], v[34:35]
	v_pk_mul_f32 v[16:17], v[18:19], v[16:17]
	v_pk_mul_f32 v[18:19], v[24:25], v[38:39] op_sel_hi:[1,0]
	v_lshlrev_b32_e32 v6, 16, v7
	v_and_b32_e32 v7, 0xffff0000, v7
	v_pk_mul_f32 v[18:19], v[106:107], v[18:19]
	v_cvt_pk_bf16_f32 v0, v0, v1
	v_cvt_pk_bf16_f32 v1, v2, v3
	v_cvt_pk_bf16_f32 v2, v8, v9
	v_cvt_pk_bf16_f32 v3, v10, v11
	v_pk_mul_f32 v[6:7], v[18:19], v[6:7]
	global_store_dwordx4 v[12:13], v[0:3], off
	s_nop 1
	v_cvt_pk_bf16_f32 v1, v4, v5
	v_add_co_u32_e32 v4, vcc, s3, v108
	v_cvt_pk_bf16_f32 v0, v14, v15
	v_cvt_pk_bf16_f32 v2, v16, v17
	v_cvt_pk_bf16_f32 v3, v6, v7
	v_addc_co_u32_e32 v5, vcc, 0, v109, vcc
	global_store_dwordx4 v[4:5], v[0:3], off offset:16
	s_add_i32 s3, 0, 0x1c620
	s_waitcnt lgkmcnt(0)
	s_barrier
; #define LAS __attribute__((address_space(3)))
; __device__ __forceinline__ float rsq_f(float x) { return __builtin_amdgcn_rsqf(x); }
; __device__ __forceinline__ float red8(float x) { x += dpp_f<0xB1>(x); x += dpp_f<0x4E>(x); x += dpp_f<0x141>(x); return x; }
; __device__ __forceinline__ void unpack8(const u32x4 u, float* x) { x[0] = bflo(u.x); x[1] = bfhi(u.x); x[2] = bflo(u.y); x[3] = bfhi(u.y); x[4] = bflo(u.z); x[5] = bfhi(u.z); x[6] = bflo(u.w); x[7] = bfhi(u.w); }
; __device__ __forceinline__ void delta_out_norm(const LAS float* ob, int pt, const float* dn16, const u32x4 z0, const u32x4 z1, bf16* dst) {
;     const LAS float* p = ob + (pt >> 3) * 132 + (pt & 7) * 16;
;     float o[16], z[16];
; #pragma unroll
;     for (int e4 = 0; e4 < 4; ++e4) { const f32x4 t = *(const LAS f32x4*)(p + 4 * e4); o[4 * e4] = t[0]; o[4 * e4 + 1] = t[1]; o[4 * e4 + 2] = t[2]; o[4 * e4 + 3] = t[3]; }
;     float ss = 0.f;
; #pragma unroll
;     for (int e = 0; e < 16; ++e) ss += o[e] * o[e];
;     ss = red8(ss);
;     const float rstd = rsq_f(ss * (1.f / 128.f) + EPS);
;     unpack8(z0, z); unpack8(z1, z + 8);
; #pragma unroll
;     for (int e = 0; e < 16; ++e) o[e] = o[e] * rstd * dn16[e] * z[e];
;     *(bf16x8*)dst = pack8(o[0], o[1], o[2], o[3], o[4], o[5], o[6], o[7]); *(bf16x8*)(dst + 8) = pack8(o[8], o[9], o[10], o[11], o[12], o[13], o[14], o[15]);
; }
; __device__ __forceinline__ void delta_rec_task(const Params& P, LAS unsigned char* lds, int b, int h, int tid) {
;     ...
;     f32x16 S[4];
; #pragma unroll
;     for (int kb = 0; kb < 4; ++kb)
; #pragma unroll
;         for (int r = 0; r < 16; ++r) S[kb][r] = 0.f;
	v_add3_u32 v12, s3, v88, v111
	ds_read_b128 v[0:3], v12
	ds_read_b128 v[4:7], v12 offset:16
	ds_read_b128 v[8:11], v12 offset:32
	ds_read_b128 v[12:15], v12 offset:48
	s_waitcnt lgkmcnt(3)
	v_mul_f32_e32 v18, v1, v1
	v_fmac_f32_e32 v18, v0, v0
	v_fmac_f32_e32 v18, v2, v2
	v_fmac_f32_e32 v18, v3, v3
	s_waitcnt lgkmcnt(2)
	v_fmac_f32_e32 v18, v4, v4
	v_fmac_f32_e32 v18, v5, v5
	v_fmac_f32_e32 v18, v6, v6
	v_fmac_f32_e32 v18, v7, v7
	s_waitcnt lgkmcnt(1)
	v_fmac_f32_e32 v18, v8, v8
	v_fmac_f32_e32 v18, v9, v9
	v_pk_mul_f32 v[16:17], v[10:11], v[10:11]
	s_nop 0
	v_add_f32_e32 v16, v16, v18
	v_add_f32_e32 v20, v17, v16
	s_waitcnt lgkmcnt(0)
	v_pk_mul_f32 v[18:19], v[12:13], v[12:13]
	v_pk_mul_f32 v[16:17], v[14:15], v[14:15]
	v_add_f32_e32 v18, v18, v20
	v_add_f32_e32 v18, v19, v18
	v_add_f32_e32 v16, v16, v18
	v_add_f32_e32 v16, v17, v16
	s_waitcnt vmcnt(3)
	v_lshlrev_b32_e32 v18, 16, v26
	v_and_b32_e32 v19, 0xffff0000, v26
	v_add_f32_dpp v16, v16, v16 quad_perm:[1,0,3,2] row_mask:0xf bank_mask:0xf bound_ctrl:1
	s_nop 1
	v_add_f32_dpp v16, v16, v16 quad_perm:[2,3,0,1] row_mask:0xf bank_mask:0xf bound_ctrl:1
	s_nop 1
	v_add_f32_dpp v16, v16, v16 row_half_mirror row_mask:0xf bank_mask:0xf bound_ctrl:1
	v_fmac_f32_e32 v40, 0x3c000000, v16
	v_rsq_f32_e32 v16, v40
	s_nop 0
	v_pk_mul_f32 v[0:1], v[0:1], v[16:17] op_sel_hi:[1,0]
	s_nop 0
	v_pk_mul_f32 v[0:1], v[102:103], v[0:1]
	v_pk_mul_f32 v[2:3], v[2:3], v[16:17] op_sel_hi:[1,0]
	v_pk_mul_f32 v[0:1], v[0:1], v[18:19]
	v_lshlrev_b32_e32 v18, 16, v27
	v_and_b32_e32 v19, 0xffff0000, v27
	v_pk_mul_f32 v[2:3], v[100:101], v[2:3]
	v_pk_mul_f32 v[4:5], v[4:5], v[16:17] op_sel_hi:[1,0]
	v_pk_mul_f32 v[2:3], v[2:3], v[18:19]
	v_lshlrev_b32_e32 v18, 16, v28
	v_and_b32_e32 v19, 0xffff0000, v28
	v_pk_mul_f32 v[4:5], v[98:99], v[4:5]
	v_pk_mul_f32 v[6:7], v[6:7], v[16:17] op_sel_hi:[1,0]
	v_pk_mul_f32 v[4:5], v[4:5], v[18:19]
	v_lshlrev_b32_e32 v18, 16, v29
	v_and_b32_e32 v19, 0xffff0000, v29
	v_pk_mul_f32 v[6:7], v[96:97], v[6:7]
	v_pk_mul_f32 v[8:9], v[8:9], v[16:17] op_sel_hi:[1,0]
	v_pk_mul_f32 v[6:7], v[6:7], v[18:19]
	s_waitcnt vmcnt(2)
	v_lshlrev_b32_e32 v18, 16, v30
	v_and_b32_e32 v19, 0xffff0000, v30
	v_pk_mul_f32 v[8:9], v[94:95], v[8:9]
	v_pk_mul_f32 v[10:11], v[10:11], v[16:17] op_sel_hi:[1,0]
	v_pk_mul_f32 v[8:9], v[8:9], v[18:19]
	v_lshlrev_b32_e32 v18, 16, v31
	v_and_b32_e32 v19, 0xffff0000, v31
	v_pk_mul_f32 v[10:11], v[92:93], v[10:11]
	v_pk_mul_f32 v[12:13], v[12:13], v[16:17] op_sel_hi:[1,0]
	v_pk_mul_f32 v[10:11], v[10:11], v[18:19]
	v_lshlrev_b32_e32 v18, 16, v32
	v_and_b32_e32 v19, 0xffff0000, v32
	v_pk_mul_f32 v[12:13], v[104:105], v[12:13]
	v_pk_mul_f32 v[14:15], v[14:15], v[16:17] op_sel_hi:[1,0]
	v_pk_mul_f32 v[12:13], v[12:13], v[18:19]
	v_lshlrev_b32_e32 v18, 16, v33
	v_and_b32_e32 v19, 0xffff0000, v33
	v_pk_mul_f32 v[14:15], v[106:107], v[14:15]
	v_cvt_pk_bf16_f32 v0, v0, v1
	v_pk_mul_f32 v[14:15], v[14:15], v[18:19]
	v_cvt_pk_bf16_f32 v1, v2, v3
	v_cvt_pk_bf16_f32 v2, v4, v5
	v_cvt_pk_bf16_f32 v3, v6, v7
	global_store_dwordx4 v[36:37], v[0:3], off
	s_nop 1
	v_cvt_pk_bf16_f32 v0, v8, v9
	v_cvt_pk_bf16_f32 v1, v10, v11
	v_cvt_pk_bf16_f32 v2, v12, v13
	v_cvt_pk_bf16_f32 v3, v14, v15
	v_mov_b32_e32 v15, 0
	global_store_dwordx4 v[36:37], v[0:3], off offset:16
	v_mov_b32_e32 v14, v15
	v_mov_b32_e32 v13, v15
	v_mov_b32_e32 v12, v15
	v_mov_b32_e32 v11, v15
	v_mov_b32_e32 v10, v15
	v_mov_b32_e32 v9, v15
	v_mov_b32_e32 v8, v15
	v_mov_b32_e32 v7, v15
	v_mov_b32_e32 v6, v15
	v_mov_b32_e32 v5, v15
	v_mov_b32_e32 v4, v15
	v_mov_b32_e32 v3, v15
	v_mov_b32_e32 v2, v15
	v_mov_b32_e32 v1, v15
	v_mov_b32_e32 v0, v15
	v_mov_b32_e32 v31, v15
	v_mov_b32_e32 v30, v15
	v_mov_b32_e32 v29, v15
	v_mov_b32_e32 v28, v15
	v_mov_b32_e32 v27, v15
	v_mov_b32_e32 v26, v15
	v_mov_b32_e32 v25, v15
	v_mov_b32_e32 v24, v15
	v_mov_b32_e32 v23, v15
	v_mov_b32_e32 v22, v15
	v_mov_b32_e32 v21, v15
	v_mov_b32_e32 v20, v15
	v_mov_b32_e32 v19, v15
	v_mov_b32_e32 v18, v15
	v_mov_b32_e32 v17, v15
	v_mov_b32_e32 v16, v15
	v_mov_b32_e32 v47, v15
	v_mov_b32_e32 v46, v15
	v_mov_b32_e32 v45, v15
	v_mov_b32_e32 v44, v15
	v_mov_b32_e32 v43, v15
	v_mov_b32_e32 v42, v15
	v_mov_b32_e32 v41, v15
	v_mov_b32_e32 v40, v15
	v_mov_b32_e32 v39, v15
	v_mov_b32_e32 v38, v15
	v_mov_b32_e32 v37, v15
	v_mov_b32_e32 v36, v15
	v_mov_b32_e32 v35, v15
	v_mov_b32_e32 v34, v15
	v_mov_b32_e32 v33, v15
	v_mov_b32_e32 v32, v15
	v_mov_b32_e32 v63, v15
	v_mov_b32_e32 v62, v15
	v_mov_b32_e32 v61, v15
	v_mov_b32_e32 v60, v15
	v_mov_b32_e32 v59, v15
	v_mov_b32_e32 v58, v15
	v_mov_b32_e32 v57, v15
	v_mov_b32_e32 v56, v15
	v_mov_b32_e32 v55, v15
	v_mov_b32_e32 v54, v15
	v_mov_b32_e32 v53, v15
	v_mov_b32_e32 v52, v15
	v_mov_b32_e32 v51, v15
	v_mov_b32_e32 v50, v15
	v_mov_b32_e32 v49, v15
	v_mov_b32_e32 v48, v15
	s_or_b64 exec, exec, s[6:7]
	s_and_saveexec_b64 s[4:5], s[8:9]
	s_cbranch_execnz .LBB0_1819
	s_branch .LBB0_1820
